# v26 + the 27-instruction correctly-rounded sqrt+divide expansions of 1/sqrt(x) in the row phases replaced by v_rsq_f32 (f32, 15 of 17 sites)
# speedup vs baseline: 1.0155x; 1.0052x over previous
.LBB0_125:
	v_lshl_add_u64 v[34:35], v[74:75], 0, s[18:19]
	s_waitcnt vmcnt(7)
	v_cvt_pk_bf16_f32 v36, v30, v31
	v_cvt_pk_bf16_f32 v37, v32, v33
	global_store_dwordx2 v[34:35], v[36:37], off
	v_mul_f32_e32 v36, v31, v31
	v_mul_f32_e32 v37, v33, v33
	v_fmac_f32_e32 v36, v30, v30
	v_fmac_f32_e32 v37, v32, v32
	v_add_f32_e32 v38, v36, v37
	s_waitcnt vmcnt(7)
	v_cvt_pk_bf16_f32 v36, v26, v27
	v_cvt_pk_bf16_f32 v37, v28, v29
	global_store_dwordx2 v[34:35], v[36:37], off offset:512
	v_mul_f32_e32 v36, v27, v27
	v_mul_f32_e32 v37, v29, v29
	v_fmac_f32_e32 v36, v26, v26
	v_fmac_f32_e32 v37, v28, v28
	v_add_f32_e32 v36, v36, v37
	v_add_f32_e32 v38, v36, v38
	s_waitcnt vmcnt(7)
	v_cvt_pk_bf16_f32 v36, v22, v23
	v_cvt_pk_bf16_f32 v37, v24, v25
	global_store_dwordx2 v[34:35], v[36:37], off offset:1024
	v_mul_f32_e32 v36, v23, v23
	v_mul_f32_e32 v37, v25, v25
	v_fmac_f32_e32 v36, v22, v22
	v_fmac_f32_e32 v37, v24, v24
	v_add_f32_e32 v36, v36, v37
	v_add_f32_e32 v38, v36, v38
	s_waitcnt vmcnt(7)
	v_cvt_pk_bf16_f32 v36, v14, v15
	v_cvt_pk_bf16_f32 v37, v16, v17
	global_store_dwordx2 v[34:35], v[36:37], off offset:1536
	v_mul_f32_e32 v36, v15, v15
	v_mul_f32_e32 v37, v17, v17
	v_fmac_f32_e32 v36, v14, v14
	v_fmac_f32_e32 v37, v16, v16
	v_add_f32_e32 v36, v36, v37
	v_add_f32_e32 v38, v36, v38
	s_waitcnt vmcnt(7)
	v_cvt_pk_bf16_f32 v36, v18, v19
	v_cvt_pk_bf16_f32 v37, v20, v21
	global_store_dwordx2 v[34:35], v[36:37], off offset:2048
	v_mul_f32_e32 v36, v19, v19
	v_mul_f32_e32 v37, v21, v21
	v_fmac_f32_e32 v36, v18, v18
	v_fmac_f32_e32 v37, v20, v20
	v_add_f32_e32 v36, v36, v37
	v_add_f32_e32 v38, v36, v38
	s_waitcnt vmcnt(7)
	v_cvt_pk_bf16_f32 v36, v10, v11
	v_cvt_pk_bf16_f32 v37, v12, v13
	global_store_dwordx2 v[34:35], v[36:37], off offset:2560
	v_mul_f32_e32 v36, v11, v11
	v_mul_f32_e32 v37, v13, v13
	v_fmac_f32_e32 v36, v10, v10
	v_fmac_f32_e32 v37, v12, v12
	v_add_f32_e32 v36, v36, v37
	v_add_f32_e32 v36, v36, v38
	s_waitcnt vmcnt(7)
	v_mul_f32_e32 v37, v7, v7
	v_mul_f32_e32 v38, v9, v9
	v_fmac_f32_e32 v37, v6, v6
	v_fmac_f32_e32 v38, v8, v8
	v_add_f32_e32 v37, v37, v38
	v_add_f32_e32 v36, v37, v36
	s_waitcnt vmcnt(6)
	v_mul_f32_e32 v37, v3, v3
	v_mul_f32_e32 v38, v5, v5
	v_fmac_f32_e32 v37, v2, v2
	v_fmac_f32_e32 v38, v4, v4
	v_add_f32_e32 v37, v37, v38
	v_add_f32_e32 v36, v37, v36
	s_nop 1
	v_add_f32_dpp v36, v36, v36 quad_perm:[1,0,3,2] row_mask:0xf bank_mask:0xf bound_ctrl:1
	s_nop 1
	v_add_f32_dpp v36, v36, v36 quad_perm:[2,3,0,1] row_mask:0xf bank_mask:0xf bound_ctrl:1
	s_nop 1
	v_add_f32_dpp v36, v36, v36 row_half_mirror row_mask:0xf bank_mask:0xf bound_ctrl:1
	s_nop 1
	v_add_f32_dpp v36, v36, v36 row_mirror row_mask:0xf bank_mask:0xf bound_ctrl:1
	s_nop 0
	v_readlane_b32 s19, v36, 16
	v_readlane_b32 s29, v36, 48
	v_readlane_b32 s18, v36, 0
	v_readlane_b32 s28, v36, 32
	v_mov_b32_e32 v36, s19
	v_mov_b32_e32 v37, s29
	v_add_f32_e32 v36, s18, v36
	v_add_f32_e32 v37, s28, v37
	v_add_f32_e32 v36, v36, v37
	v_fmamk_f32 v36, v36, 0x3a000000, v1
	s_nop 1
	v_rsq_f32_e32 v38, v36
	v_cvt_pk_bf16_f32 v36, v6, v7
	v_cvt_pk_bf16_f32 v37, v8, v9
	global_store_dwordx2 v[34:35], v[36:37], off offset:3072
	s_nop 0
	s_nop 1
	s_nop 1
	v_cvt_pk_bf16_f32 v36, v2, v3
	v_cvt_pk_bf16_f32 v37, v4, v5
	global_store_dwordx2 v[34:35], v[36:37], off offset:3584
	v_mov_b32_e32 v76, v38
	s_and_saveexec_b64 s[18:19], s[0:1]
	s_cbranch_execz .LBB0_127
	s_lshl_b64 s[28:29], s[40:41], 2
	v_readlane_b32 s41, v245, 9
	s_add_u32 s28, s41, s28
	v_readlane_b32 s41, v245, 10
	s_addc_u32 s29, s41, s29
	global_store_dword v67, v76, s[28:29]

.LBB0_131:
	s_waitcnt vmcnt(7)
	v_pk_mul_f32 v[92:93], v[62:63], v[62:63]
	s_waitcnt vmcnt(6)
	v_pk_mul_f32 v[94:95], v[58:59], v[58:59]
	v_pk_mul_f32 v[88:89], v[64:65], v[64:65]
	v_pk_mul_f32 v[90:91], v[60:61], v[60:61]
	v_mov_b32_e32 v96, v92
	v_mov_b32_e32 v97, v94
	v_mov_b32_e32 v94, v93
	v_lshl_add_u64 v[78:79], v[74:75], 0, s[18:19]
	v_cvt_pk_bf16_f32 v80, v62, v63
	v_cvt_pk_bf16_f32 v81, v64, v65
	v_pk_add_f32 v[92:93], v[96:97], v[94:95]
	v_mov_b32_e32 v94, v88
	v_mov_b32_e32 v95, v90
	v_mov_b32_e32 v90, v89
	global_store_dwordx2 v[78:79], v[80:81], off
	v_cvt_pk_bf16_f32 v80, v58, v59
	v_cvt_pk_bf16_f32 v81, v60, v61
	global_store_dwordx2 v[78:79], v[80:81], off offset:512
	s_waitcnt vmcnt(7)
	v_pk_mul_f32 v[84:85], v[56:57], v[56:57]
	v_pk_mul_f32 v[86:87], v[54:55], v[54:55]
	v_pk_add_f32 v[88:89], v[94:95], v[90:91]
	v_cvt_pk_bf16_f32 v90, v54, v55
	v_cvt_pk_bf16_f32 v91, v56, v57
	global_store_dwordx2 v[78:79], v[90:91], off offset:1024
	v_pk_mov_b32 v[90:91], v[86:87], v[84:85] op_sel:[1,0]
	v_mov_b32_e32 v87, v85
	v_pk_add_f32 v[84:85], v[90:91], v[86:87]
	s_waitcnt vmcnt(7)
	v_cvt_pk_bf16_f32 v86, v46, v47
	v_cvt_pk_bf16_f32 v87, v48, v49
	v_pk_add_f32 v[88:89], v[92:93], v[88:89]
	v_pk_add_f32 v[84:85], v[84:85], v[84:85] op_sel_hi:[0,1]
	v_mul_f32_e32 v84, v46, v46
	global_store_dwordx2 v[78:79], v[86:87], off offset:1536
	v_pk_fma_f32 v[86:87], v[46:47], v[46:47], v[84:85] op_sel_hi:[1,1,0]
	v_mul_f32_e32 v84, v48, v48
	v_pk_add_f32 v[88:89], v[88:89], v[88:89] op_sel_hi:[0,1]
	v_pk_fma_f32 v[90:91], v[48:49], v[48:49], v[84:85] op_sel_hi:[1,1,0]
	s_waitcnt vmcnt(7)
	v_mul_f32_e32 v86, v50, v50
	v_mul_f32_e32 v90, v51, v51
	v_mul_f32_e32 v84, v52, v52
	v_mul_f32_e32 v88, v53, v53
	v_pk_add_f32 v[86:87], v[86:87], v[90:91]
	v_pk_add_f32 v[84:85], v[84:85], v[88:89]
	s_waitcnt vmcnt(6)
	v_pk_mul_f32 v[80:81], v[44:45], v[44:45]
	v_pk_mul_f32 v[82:83], v[42:43], v[42:43]
	v_cvt_pk_bf16_f32 v92, v50, v51
	v_cvt_pk_bf16_f32 v93, v52, v53
	global_store_dwordx2 v[78:79], v[92:93], off offset:2048
	v_pk_add_f32 v[84:85], v[86:87], v[84:85]
	v_cvt_pk_bf16_f32 v86, v42, v43
	v_cvt_pk_bf16_f32 v87, v44, v45
	global_store_dwordx2 v[78:79], v[86:87], off offset:2560
	v_pk_mov_b32 v[86:87], v[82:83], v[80:81] op_sel:[1,0]
	v_mov_b32_e32 v83, v81
	v_pk_add_f32 v[80:81], v[86:87], v[82:83]
	v_pk_add_f32 v[84:85], v[84:85], v[84:85] op_sel_hi:[0,1]
	v_pk_add_f32 v[80:81], v[80:81], v[80:81] op_sel_hi:[0,1]
	s_waitcnt vmcnt(7)
	v_mul_f32_e32 v80, v38, v38
	v_pk_fma_f32 v[82:83], v[38:39], v[38:39], v[80:81] op_sel_hi:[1,1,0]
	v_mul_f32_e32 v80, v40, v40
	v_pk_fma_f32 v[86:87], v[40:41], v[40:41], v[80:81] op_sel_hi:[1,1,0]
	s_waitcnt vmcnt(6)
	v_mul_f32_e32 v82, v34, v34
	v_mul_f32_e32 v86, v35, v35
	v_mul_f32_e32 v80, v36, v36
	v_mul_f32_e32 v84, v37, v37
	v_pk_add_f32 v[82:83], v[82:83], v[86:87]
	v_pk_add_f32 v[80:81], v[80:81], v[84:85]
	s_nop 0
	v_pk_add_f32 v[80:81], v[82:83], v[80:81]
	s_nop 0
	v_add_f32_e32 v77, v80, v81
	s_nop 1
	v_add_f32_dpp v77, v77, v77 quad_perm:[1,0,3,2] row_mask:0xf bank_mask:0xf bound_ctrl:1
	s_nop 1
	v_add_f32_dpp v77, v77, v77 quad_perm:[2,3,0,1] row_mask:0xf bank_mask:0xf bound_ctrl:1
	s_nop 1
	v_add_f32_dpp v77, v77, v77 row_half_mirror row_mask:0xf bank_mask:0xf bound_ctrl:1
	s_nop 1
	v_add_f32_dpp v77, v77, v77 row_mirror row_mask:0xf bank_mask:0xf bound_ctrl:1
	s_nop 0
	v_readlane_b32 s41, v77, 16
	v_readlane_b32 s44, v77, 48
	v_readlane_b32 s18, v77, 0
	v_readlane_b32 s19, v77, 32
	v_mov_b32_e32 v80, s41
	v_mov_b32_e32 v81, s44
	v_pk_add_f32 v[80:81], s[18:19], v[80:81]
	s_nop 0
	v_add_f32_e32 v77, v80, v81
	v_fmamk_f32 v77, v77, 0x3a000000, v1
	s_nop 1
	v_rsq_f32_e32 v77, v77
	v_cvt_pk_bf16_f32 v80, v38, v39
	v_cvt_pk_bf16_f32 v81, v40, v41
	global_store_dwordx2 v[78:79], v[80:81], off offset:3072
	s_nop 0
	s_nop 1
	s_nop 1
	v_cvt_pk_bf16_f32 v80, v34, v35
	v_cvt_pk_bf16_f32 v81, v36, v37
	global_store_dwordx2 v[78:79], v[80:81], off offset:3584
	v_mov_b32_e32 v77, v77
	s_and_saveexec_b64 s[18:19], s[0:1]
	s_cbranch_execz .LBB0_133
	s_lshl_b64 s[44:45], s[28:29], 2
	v_readlane_b32 s29, v245, 9
	s_add_u32 s44, s29, s44
	v_readlane_b32 s29, v245, 10
	s_addc_u32 s45, s29, s45
	global_store_dword v67, v77, s[44:45]

.LBB0_1031:
	v_readlane_b32 s36, v246, 5
	v_readlane_b32 s40, v246, 9
	v_readlane_b32 s41, v246, 10
	v_readlane_b32 s42, v246, 11
	v_readlane_b32 s43, v246, 12
	s_mov_b64 s[20:21], s[40:41]
	v_lshl_add_u64 v[62:63], s[20:21], 0, v[56:57]
	global_load_dwordx2 v[34:35], v[62:63], off offset:1024
	global_load_dwordx2 v[36:37], v[62:63], off offset:2560
	global_load_dwordx2 v[38:39], v[62:63], off offset:1536
	global_load_dwordx2 v[40:41], v[62:63], off offset:3072
	global_load_dwordx2 v[42:43], v[62:63], off offset:2048
	global_load_dwordx2 v[44:45], v[62:63], off offset:3584
	s_add_i32 s2, s86, s8
	s_cmp_lt_i32 s2, s25
	s_cselect_b32 s4, s2, s8
	s_ashr_i32 s5, s4, 31
	s_lshl_b64 s[0:1], s[4:5], 12
	v_readlane_b32 s38, v246, 7
	v_readlane_b32 s39, v246, 8
	v_readlane_b32 s37, v246, 6
	s_lshl_b64 s[4:5], s[4:5], 11
	s_waitcnt vmcnt(19)
	v_lshl_add_u64 v[46:47], v[50:51], 0, s[4:5]
	s_waitcnt vmcnt(13)
	v_lshl_add_u64 v[94:95], v[52:53], 0, s[0:1]
	s_cmp_ge_i32 s2, s25
	s_mov_b64 s[22:23], s[42:43]
	s_waitcnt vmcnt(5)
	v_lshlrev_b32_e32 v88, 16, v34
	v_and_b32_e32 v89, 0xffff0000, v34
	v_mul_f32_e32 v66, v88, v88
	v_mul_f32_e32 v34, v89, v89
	s_waitcnt vmcnt(1)
	v_lshlrev_b32_e32 v67, 16, v42
	v_and_b32_e32 v92, 0xffff0000, v35
	v_lshlrev_b32_e32 v93, 16, v35
	v_lshlrev_b32_e32 v80, 16, v38
	v_and_b32_e32 v81, 0xffff0000, v38
	v_and_b32_e32 v83, s0, v39
	v_and_b32_e32 v82, 0xffff0000, v39
	v_lshlrev_b32_e32 v85, 16, v39
	v_mov_b32_e32 v35, v67
	v_pk_mul_f32 v[38:39], v[66:67], v[66:67]
	v_and_b32_e32 v75, 0xffff0000, v42
	v_pk_add_f32 v[34:35], v[66:67], v[34:35]
	v_mul_f32_e32 v38, v93, v93
	v_lshlrev_b32_e32 v90, 16, v37
	v_and_b32_e32 v91, 0xffff0000, v37
	v_mul_f32_e32 v37, v75, v75
	v_mov_b32_e32 v35, v39
	v_pk_fma_f32 v[38:39], v[92:93], v[92:93], v[38:39] op_sel_hi:[1,1,0]
	v_and_b32_e32 v73, 0xffff0000, v43
	v_mov_b32_e32 v39, v37
	v_pk_add_f32 v[34:35], v[34:35], v[38:39]
	v_mul_f32_e32 v38, v81, v81
	v_lshlrev_b32_e32 v76, 16, v40
	v_and_b32_e32 v77, 0xffff0000, v40
	v_mul_f32_e32 v40, v73, v73
	v_pk_fma_f32 v[38:39], v[80:81], v[80:81], v[38:39] op_sel_hi:[1,1,0]
	v_mov_b32_e32 v84, v82
	v_lshlrev_b32_e32 v72, 16, v43
	v_mov_b32_e32 v39, v40
	v_mul_f32_e32 v40, v85, v85
	v_lshlrev_b32_e32 v78, 16, v41
	v_and_b32_e32 v79, 0xffff0000, v41
	v_mul_f32_e32 v42, v72, v72
	v_pk_fma_f32 v[40:41], v[84:85], v[84:85], v[40:41] op_sel_hi:[1,1,0]
	v_lshlrev_b32_e32 v86, 16, v36
	v_mov_b32_e32 v41, v42
	v_and_b32_e32 v87, 0xffff0000, v36
	s_waitcnt vmcnt(0)
	v_lshlrev_b32_e32 v65, 16, v44
	v_pk_add_f32 v[38:39], v[38:39], v[40:41]
	v_mul_f32_e32 v64, v86, v86
	v_mul_f32_e32 v36, v87, v87
	v_pk_add_f32 v[34:35], v[34:35], v[38:39]
	v_mov_b32_e32 v37, v65
	v_add_f32_e32 v40, v34, v35
	v_pk_add_f32 v[34:35], v[64:65], v[36:37]
	v_pk_mul_f32 v[36:37], v[64:65], v[64:65]
	v_and_b32_e32 v71, 0xffff0000, v44
	v_mul_f32_e32 v36, v91, v91
	v_mul_f32_e32 v38, v71, v71
	v_mov_b32_e32 v35, v37
	v_pk_fma_f32 v[36:37], v[90:91], v[90:91], v[36:37] op_sel_hi:[1,1,0]
	v_lshlrev_b32_e32 v68, 16, v45
	v_mov_b32_e32 v37, v38
	v_pk_add_f32 v[34:35], v[34:35], v[36:37]
	v_mul_f32_e32 v36, v77, v77
	v_and_b32_e32 v69, 0xffff0000, v45
	v_mul_f32_e32 v39, v68, v68
	v_pk_fma_f32 v[36:37], v[76:77], v[76:77], v[36:37] op_sel_hi:[1,1,0]
	v_mul_f32_e32 v38, v79, v79
	v_mul_f32_e32 v41, v69, v69
	v_mov_b32_e32 v37, v39
	v_pk_fma_f32 v[38:39], v[78:79], v[78:79], v[38:39] op_sel_hi:[1,1,0]
	s_nop 0
	v_mov_b32_e32 v39, v41
	v_pk_add_f32 v[36:37], v[36:37], v[38:39]
	v_lshl_add_u64 v[38:39], s[20:21], 0, v[54:55]
	v_pk_add_f32 v[34:35], v[34:35], v[36:37]
	s_nop 0
	v_add_f32_e32 v36, v34, v35
	v_add_f32_dpp v34, v40, v40 quad_perm:[1,0,3,2] row_mask:0xf bank_mask:0xf bound_ctrl:1
	s_nop 1
	v_add_f32_dpp v34, v34, v34 quad_perm:[2,3,0,1] row_mask:0xf bank_mask:0xf bound_ctrl:1
	s_nop 1
	v_add_f32_dpp v34, v34, v34 row_half_mirror row_mask:0xf bank_mask:0xf bound_ctrl:1
	s_nop 1
	v_add_f32_dpp v34, v34, v34 row_mirror row_mask:0xf bank_mask:0xf bound_ctrl:1
	s_nop 0
	v_readlane_b32 s3, v34, 16
	v_readlane_b32 s9, v34, 48
	v_readlane_b32 s18, v34, 0
	v_readlane_b32 s19, v34, 32
	v_mov_b32_e32 v34, s3
	v_mov_b32_e32 v35, s9
	v_pk_add_f32 v[34:35], s[18:19], v[34:35]
	s_nop 0
	v_add_f32_e32 v34, v34, v35
	v_fmamk_f32 v34, v34, 0x3aaaaaab, v173
	v_cmp_gt_f32_e64 s[38:39], s92, v34
	v_mul_f32_e32 v35, 0x4f800000, v34
	s_nop 0
	v_cndmask_b32_e64 v74, v34, v35, s[38:39]
	v_add_f32_dpp v34, v36, v36 quad_perm:[1,0,3,2] row_mask:0xf bank_mask:0xf bound_ctrl:1
	v_sqrt_f32_e32 v109, v74
	s_nop 0
	v_add_f32_dpp v34, v34, v34 quad_perm:[2,3,0,1] row_mask:0xf bank_mask:0xf bound_ctrl:1
	v_add_u32_e32 v110, -1, v109
	s_nop 0
	v_add_f32_dpp v34, v34, v34 row_half_mirror row_mask:0xf bank_mask:0xf bound_ctrl:1
	v_add_u32_e32 v108, 1, v109
	s_nop 0
	v_add_f32_dpp v34, v34, v34 row_mirror row_mask:0xf bank_mask:0xf bound_ctrl:1
	s_nop 0
	v_readlane_b32 s3, v34, 16
	v_readlane_b32 s9, v34, 48
	v_readlane_b32 s18, v34, 0
	v_readlane_b32 s19, v34, 32
	v_mov_b32_e32 v34, s3
	v_mov_b32_e32 v35, s9
	v_pk_add_f32 v[34:35], s[18:19], v[34:35]
	s_nop 0
	v_add_f32_e32 v34, v34, v35
	v_fmamk_f32 v34, v34, 0x3aaaaaab, v173
	v_cmp_gt_f32_e64 s[36:37], s92, v34
	v_mul_f32_e32 v35, 0x4f800000, v34
	s_nop 0
	v_cndmask_b32_e64 v61, v34, v35, s[36:37]
	global_load_dwordx4 v[34:37], v[38:39], off offset:-256
	s_nop 0
	global_load_dwordx4 v[38:41], v[38:39], off
	s_nop 0
	global_load_dwordx4 v[42:45], v[46:47], off
	s_nop 0
	global_load_dwordx4 v[46:49], v[46:47], off offset:256
	s_nop 0
	global_load_dwordx2 v[104:105], v[94:95], off offset:1024
	global_load_dwordx2 v[102:103], v[94:95], off offset:2560
	global_load_dwordx2 v[100:101], v[94:95], off offset:1536
	global_load_dwordx2 v[98:99], v[94:95], off offset:3072
	global_load_dwordx2 v[96:97], v[94:95], off offset:2048
	s_nop 0
	global_load_dwordx2 v[94:95], v[94:95], off offset:3584
	v_sqrt_f32_e32 v66, v61
	s_waitcnt vmcnt(9)
	v_lshlrev_b32_e32 v111, 16, v34
	s_waitcnt vmcnt(8)
	v_lshlrev_b32_e32 v112, 16, v38
	v_and_b32_e32 v34, 0xffff0000, v34
	v_and_b32_e32 v38, 0xffff0000, v38
	v_fma_f32 v111, -v106, v112, v111
	v_fma_f32 v34, -v106, v38, v34
	v_lshlrev_b32_e32 v38, 16, v35
	v_lshlrev_b32_e32 v112, 16, v39
	v_and_b32_e32 v35, 0xffff0000, v35
	v_and_b32_e32 v39, 0xffff0000, v39
	v_fma_f32 v38, -v106, v112, v38
	v_fma_f32 v35, -v106, v39, v35
	v_lshlrev_b32_e32 v39, 16, v36
	v_lshlrev_b32_e32 v112, 16, v40
	v_and_b32_e32 v36, 0xffff0000, v36
	v_and_b32_e32 v40, 0xffff0000, v40
	v_fma_f32 v39, -v106, v112, v39
	v_fma_f32 v36, -v106, v40, v36
	v_lshlrev_b32_e32 v40, 16, v37
	v_lshlrev_b32_e32 v112, 16, v41
	v_and_b32_e32 v37, 0xffff0000, v37
	v_and_b32_e32 v41, 0xffff0000, v41
	v_fma_f32 v37, -v106, v41, v37
	v_mul_f32_e32 v41, v34, v34
	v_fmac_f32_e32 v41, v111, v111
	v_fmac_f32_e32 v41, v38, v38
	v_fmac_f32_e32 v41, v35, v35
	v_fmac_f32_e32 v41, v39, v39
	v_fma_f32 v40, -v106, v112, v40
	v_fmac_f32_e32 v41, v36, v36
	v_fmac_f32_e32 v41, v40, v40
	v_fmac_f32_e32 v41, v37, v37
	v_add_u32_e32 v70, -1, v66
	v_add_u32_e32 v64, 1, v66
	v_add_f32_dpp v41, v41, v41 quad_perm:[1,0,3,2] row_mask:0xf bank_mask:0xf bound_ctrl:1
	s_nop 1
	v_add_f32_dpp v41, v41, v41 quad_perm:[2,3,0,1] row_mask:0xf bank_mask:0xf bound_ctrl:1
	s_nop 1
	v_add_f32_dpp v41, v41, v41 row_half_mirror row_mask:0xf bank_mask:0xf bound_ctrl:1
	s_nop 1
	v_add_f32_dpp v41, v41, v41 row_mirror row_mask:0xf bank_mask:0xf bound_ctrl:1
	v_fmamk_f32 v41, v41, 0x3c000000, v173
	v_cmp_gt_f32_e32 vcc, s92, v41
	s_nop 0
	v_rsq_f32_e32 v41, v41
	s_nop 0
	s_nop 0
	s_nop 1
	s_nop 1
	s_nop 0
	v_mul_f32_e32 v41, v1, v41
	v_mul_f32_e32 v34, v34, v41
	v_mul_f32_e32 v38, v38, v41
	v_mul_f32_e32 v35, v35, v41
	v_mul_f32_e32 v111, v111, v41
	v_mul_f32_e32 v34, v27, v34
	v_mul_f32_e32 v38, v28, v38
	v_mul_f32_e32 v35, v29, v35
	v_mul_f32_e32 v111, v26, v111
	v_cvt_pk_bf16_f32 v34, v111, v34
	v_cvt_pk_bf16_f32 v35, v38, v35
	v_mul_f32_e32 v38, v39, v41
	v_mul_f32_e32 v36, v36, v41
	v_mul_f32_e32 v38, v30, v38
	v_mul_f32_e32 v36, v31, v36
	v_cvt_pk_bf16_f32 v36, v38, v36
	v_mul_f32_e32 v38, v40, v41
	v_mul_f32_e32 v37, v37, v41
	v_mul_f32_e32 v38, v32, v38
	v_mul_f32_e32 v37, v33, v37
	v_cvt_pk_bf16_f32 v37, v38, v37
	v_lshl_add_u64 v[38:39], s[20:21], 0, v[58:59]
	global_store_dwordx4 v[38:39], v[34:37], off
	s_nop 1
	v_fma_f32 v34, -v110, v109, v74
	v_cmp_ge_f32_e32 vcc, 0, v34
	v_fma_f32 v35, -v108, v109, v74
	s_nop 0
	v_cndmask_b32_e32 v34, v109, v110, vcc
	v_cmp_lt_f32_e32 vcc, 0, v35
	s_nop 1
	v_cndmask_b32_e32 v34, v34, v108, vcc
	v_mul_f32_e32 v35, 0x37800000, v34
	v_cndmask_b32_e64 v34, v34, v35, s[38:39]
	v_cmp_class_f32_e32 vcc, v74, v174
	s_nop 1
	v_cndmask_b32_e32 v34, v34, v74, vcc
	v_div_scale_f32 v35, s[0:1], v34, v34, 1.0
	v_rcp_f32_e32 v36, v35
	v_mov_b32_e32 v74, v67
	v_fma_f32 v37, -v35, v36, 1.0
	v_fmac_f32_e32 v36, v37, v36
	v_div_scale_f32 v37, vcc, 1.0, v34, 1.0
	v_mul_f32_e32 v38, v37, v36
	v_fma_f32 v39, -v35, v38, v37
	v_fmac_f32_e32 v38, v39, v36
	v_fma_f32 v35, -v35, v38, v37
	v_div_fmas_f32 v35, v35, v36, v38
	v_div_fixup_f32 v34, v35, v34, 1.0
	v_fma_f32 v35, -v70, v66, v61
	v_cmp_ge_f32_e32 vcc, 0, v35
	v_fma_f32 v36, -v64, v66, v61
	s_nop 0
	v_cndmask_b32_e32 v35, v66, v70, vcc
	v_cmp_lt_f32_e32 vcc, 0, v36
	v_mov_b32_e32 v70, v65
	s_nop 0
	v_cndmask_b32_e32 v35, v35, v64, vcc
	v_mul_f32_e32 v36, 0x37800000, v35
	v_cndmask_b32_e64 v35, v35, v36, s[36:37]
	v_cmp_class_f32_e32 vcc, v61, v174
	s_nop 1
	v_cndmask_b32_e32 v35, v35, v61, vcc
	v_div_scale_f32 v36, s[0:1], v35, v35, 1.0
	v_rcp_f32_e32 v37, v36
	s_nop 0
	v_fma_f32 v38, -v36, v37, 1.0
	v_fmac_f32_e32 v37, v38, v37
	v_div_scale_f32 v38, vcc, 1.0, v35, 1.0
	v_mul_f32_e32 v39, v38, v37
	v_fma_f32 v40, -v36, v39, v38
	v_fmac_f32_e32 v39, v40, v37
	v_fma_f32 v36, -v36, v39, v38
	v_div_fmas_f32 v36, v36, v37, v39
	v_pk_mul_f32 v[38:39], v[88:89], v[34:35] op_sel_hi:[1,0]
	v_div_fixup_f32 v36, v36, v35, 1.0
	v_pk_mul_f32 v[40:41], v[92:93], v[34:35] op_sel:[1,0] op_sel_hi:[0,0]
	v_pk_mul_f32 v[38:39], v[2:3], v[38:39]
	v_pk_mul_f32 v[40:41], v[4:5], v[40:41]
	v_pk_mul_f32 v[86:87], v[86:87], v[36:37] op_sel_hi:[1,0]
	v_pk_mul_f32 v[88:89], v[90:91], v[36:37] op_sel_hi:[1,0]
	v_cvt_pk_bf16_f32 v38, v38, v39
	v_cvt_pk_bf16_f32 v39, v40, v41
	v_pk_mul_f32 v[86:87], v[6:7], v[86:87]
	v_pk_mul_f32 v[88:89], v[8:9], v[88:89]
	global_store_dwordx2 v[62:63], v[38:39], off offset:1024
	v_cvt_pk_bf16_f32 v38, v86, v87
	v_cvt_pk_bf16_f32 v39, v88, v89
	global_store_dwordx2 v[62:63], v[38:39], off offset:2560
	v_pk_mul_f32 v[38:39], v[34:35], v[80:81] op_sel_hi:[0,1]
	v_pk_mov_b32 v[40:41], v[84:85], v[82:83] op_sel:[1,0]
	v_pk_mul_f32 v[38:39], v[10:11], v[38:39]
	v_pk_mul_f32 v[40:41], v[34:35], v[40:41] op_sel_hi:[0,1]
	v_pk_mul_f32 v[40:41], v[12:13], v[40:41]
	v_pk_mul_f32 v[76:77], v[36:37], v[76:77] op_sel_hi:[0,1]
	v_pk_mul_f32 v[78:79], v[36:37], v[78:79] op_sel_hi:[0,1]
	v_cvt_pk_bf16_f32 v38, v38, v39
	v_cvt_pk_bf16_f32 v39, v40, v41
	v_pk_mul_f32 v[78:79], v[16:17], v[78:79]
	v_pk_mul_f32 v[76:77], v[14:15], v[76:77]
	global_store_dwordx2 v[62:63], v[38:39], off offset:1536
	v_cvt_pk_bf16_f32 v38, v76, v77
	v_cvt_pk_bf16_f32 v39, v78, v79
	global_store_dwordx2 v[62:63], v[38:39], off offset:3072
	v_pk_mul_f32 v[38:39], v[74:75], v[34:35] op_sel_hi:[1,0]
	v_pk_mul_f32 v[34:35], v[72:73], v[34:35] op_sel_hi:[1,0]
	v_pk_mul_f32 v[38:39], v[18:19], v[38:39]
	v_pk_mul_f32 v[34:35], v[20:21], v[34:35]
	v_pk_mul_f32 v[40:41], v[70:71], v[36:37] op_sel_hi:[1,0]
	v_pk_mul_f32 v[36:37], v[68:69], v[36:37] op_sel_hi:[1,0]
	v_pk_mul_f32 v[40:41], v[22:23], v[40:41]
	v_pk_mul_f32 v[36:37], v[24:25], v[36:37]
	v_cvt_pk_bf16_f32 v38, v38, v39
	v_cvt_pk_bf16_f32 v39, v34, v35
	global_store_dwordx2 v[62:63], v[38:39], off offset:2048
	v_cvt_pk_bf16_f32 v34, v40, v41
	v_cvt_pk_bf16_f32 v35, v36, v37
	global_store_dwordx2 v[62:63], v[34:35], off offset:3584
	s_cbranch_scc1 .LBB0_1030
	s_waitcnt vmcnt(14)
	v_lshlrev_b32_e32 v34, 16, v42
	s_waitcnt vmcnt(13)
	v_lshlrev_b32_e32 v35, 16, v46
	v_fma_f32 v34, -v106, v35, v34
	v_and_b32_e32 v35, 0xffff0000, v42
	v_and_b32_e32 v36, 0xffff0000, v46
	v_fma_f32 v35, -v106, v36, v35
	v_lshlrev_b32_e32 v36, 16, v43
	v_lshlrev_b32_e32 v37, 16, v47
	v_fma_f32 v36, -v106, v37, v36
	v_and_b32_e32 v37, 0xffff0000, v43
	v_and_b32_e32 v38, 0xffff0000, v47
	v_fma_f32 v37, -v106, v38, v37
	v_lshlrev_b32_e32 v38, 16, v44
	v_lshlrev_b32_e32 v39, 16, v48
	v_fma_f32 v38, -v106, v39, v38
	v_and_b32_e32 v39, 0xffff0000, v44
	v_and_b32_e32 v40, 0xffff0000, v48
	v_fma_f32 v39, -v106, v40, v39
	v_lshlrev_b32_e32 v40, 16, v45
	v_lshlrev_b32_e32 v41, 16, v49
	v_fma_f32 v40, -v106, v41, v40
	v_and_b32_e32 v41, 0xffff0000, v45
	v_and_b32_e32 v42, 0xffff0000, v49
	v_fma_f32 v41, -v106, v42, v41
	v_mul_f32_e32 v42, v35, v35
	v_fmac_f32_e32 v42, v34, v34
	v_fmac_f32_e32 v42, v36, v36
	v_fmac_f32_e32 v42, v37, v37
	v_fmac_f32_e32 v42, v38, v38
	v_fmac_f32_e32 v42, v39, v39
	v_fmac_f32_e32 v42, v40, v40
	v_fmac_f32_e32 v42, v41, v41
	s_ashr_i32 s3, s2, 31
	s_lshl_b64 s[0:1], s[2:3], 12
	v_add_f32_dpp v42, v42, v42 quad_perm:[1,0,3,2] row_mask:0xf bank_mask:0xf bound_ctrl:1
	v_readlane_b32 s2, v245, 30
	v_readlane_b32 s3, v245, 31
	v_add_f32_dpp v42, v42, v42 quad_perm:[2,3,0,1] row_mask:0xf bank_mask:0xf bound_ctrl:1
	s_add_u32 s2, s2, s0
	s_addc_u32 s3, s3, s1
	v_add_f32_dpp v42, v42, v42 row_half_mirror row_mask:0xf bank_mask:0xf bound_ctrl:1
	v_mov_b32_e32 v61, v163
	s_waitcnt vmcnt(12)
	v_lshlrev_b32_e32 v70, 16, v104
	v_add_f32_dpp v42, v42, v42 row_mirror row_mask:0xf bank_mask:0xf bound_ctrl:1
	v_fmamk_f32 v42, v42, 0x3c000000, v173
	v_cmp_gt_f32_e32 vcc, s92, v42
	v_and_b32_e32 v71, 0xffff0000, v104
	v_rsq_f32_e32 v42, v42
	v_mul_f32_e32 v76, v71, v71
	v_lshlrev_b32_e32 v75, 16, v105
	v_and_b32_e32 v74, 0xffff0000, v105
	s_waitcnt vmcnt(10)
	v_and_b32_e32 v48, 0xffff0000, v101
	v_lshlrev_b32_e32 v65, 16, v101
	v_mov_b32_e32 v64, v48
	v_lshlrev_b32_e32 v66, 16, v102
	v_and_b32_e32 v67, 0xffff0000, v102
	v_mul_f32_e32 v78, v67, v67
	v_and_b32_e32 v73, 0xffff0000, v103
	v_lshlrev_b32_e32 v72, 16, v103
	v_mul_f32_e32 v42, v1, v42
	v_mul_f32_e32 v34, v34, v42
	v_mul_f32_e32 v35, v35, v42
	v_mul_f32_e32 v34, v26, v34
	v_mul_f32_e32 v35, v27, v35
	v_cvt_pk_bf16_f32 v34, v34, v35
	v_mul_f32_e32 v35, v36, v42
	v_mul_f32_e32 v36, v37, v42
	v_mul_f32_e32 v35, v28, v35
	v_mul_f32_e32 v36, v29, v36
	v_cvt_pk_bf16_f32 v35, v35, v36
	v_mul_f32_e32 v36, v38, v42
	v_mul_f32_e32 v37, v39, v42
	v_mul_f32_e32 v36, v30, v36
	v_mul_f32_e32 v37, v31, v37
	v_cvt_pk_bf16_f32 v36, v36, v37
	v_mul_f32_e32 v37, v40, v42
	v_mul_f32_e32 v38, v41, v42
	v_mul_f32_e32 v37, v32, v37
	v_mul_f32_e32 v38, v33, v38
	v_cvt_pk_bf16_f32 v37, v37, v38
	v_lshl_add_u64 v[38:39], s[2:3], 0, v[162:163]
	v_lshl_add_u64 v[38:39], v[38:39], 0, v[60:61]
	global_store_dwordx4 v[38:39], v[34:37], off
	s_waitcnt vmcnt(9)
	v_and_b32_e32 v45, 0xffff0000, v96
	v_and_b32_e32 v47, 0xffff0000, v100
	v_lshlrev_b32_e32 v37, 16, v96
	v_mul_f32_e32 v36, v70, v70
	v_mov_b32_e32 v77, v37
	v_pk_add_f32 v[76:77], v[36:37], v[76:77]
	v_pk_mul_f32 v[80:81], v[36:37], v[36:37]
	v_mul_f32_e32 v36, v75, v75
	v_mul_f32_e32 v40, v45, v45
	v_mov_b32_e32 v77, v81
	v_pk_fma_f32 v[80:81], v[74:75], v[74:75], v[36:37] op_sel_hi:[1,1,0]
	v_lshlrev_b32_e32 v46, 16, v100
	v_mov_b32_e32 v81, v40
	v_mul_f32_e32 v36, v47, v47
	v_lshlrev_b32_e32 v42, 16, v97
	v_and_b32_e32 v43, 0xffff0000, v97
	v_pk_add_f32 v[76:77], v[76:77], v[80:81]
	v_pk_fma_f32 v[80:81], v[46:47], v[46:47], v[36:37] op_sel_hi:[1,1,0]
	v_mul_f32_e32 v36, v65, v65
	v_mul_f32_e32 v44, v42, v42
	v_mul_f32_e32 v61, v43, v43
	v_pk_fma_f32 v[82:83], v[64:65], v[64:65], v[36:37] op_sel_hi:[1,1,0]
	v_mov_b32_e32 v81, v61
	v_mov_b32_e32 v83, v44
	s_waitcnt vmcnt(8)
	v_lshlrev_b32_e32 v35, 16, v94
	v_pk_add_f32 v[80:81], v[80:81], v[82:83]
	v_mul_f32_e32 v34, v66, v66
	v_pk_add_f32 v[76:77], v[76:77], v[80:81]
	v_mov_b32_e32 v79, v35
	v_and_b32_e32 v41, 0xffff0000, v94
	v_add_f32_e32 v36, v76, v77
	v_pk_add_f32 v[76:77], v[34:35], v[78:79]
	v_pk_mul_f32 v[78:79], v[34:35], v[34:35]
	v_mul_f32_e32 v34, v73, v73
	v_and_b32_e32 v63, 0xffff0000, v98
	v_mul_f32_e32 v40, v41, v41
	v_mov_b32_e32 v77, v79
	v_pk_fma_f32 v[78:79], v[72:73], v[72:73], v[34:35] op_sel_hi:[1,1,0]
	v_lshlrev_b32_e32 v62, 16, v98
	v_and_b32_e32 v69, 0xffff0000, v99
	v_mov_b32_e32 v79, v40
	v_mul_f32_e32 v34, v63, v63
	v_lshlrev_b32_e32 v68, 16, v99
	v_pk_add_f32 v[76:77], v[76:77], v[78:79]
	v_pk_fma_f32 v[78:79], v[62:63], v[62:63], v[34:35] op_sel_hi:[1,1,0]
	v_mul_f32_e32 v34, v69, v69
	v_lshlrev_b32_e32 v38, 16, v95
	v_and_b32_e32 v39, 0xffff0000, v95
	v_pk_fma_f32 v[80:81], v[68:69], v[68:69], v[34:35] op_sel_hi:[1,1,0]
	v_add_f32_dpp v34, v36, v36 quad_perm:[1,0,3,2] row_mask:0xf bank_mask:0xf bound_ctrl:1
	v_mul_f32_e32 v44, v38, v38
	v_mul_f32_e32 v61, v39, v39
	v_add_f32_dpp v34, v34, v34 quad_perm:[2,3,0,1] row_mask:0xf bank_mask:0xf bound_ctrl:1
	v_mov_b32_e32 v79, v44
	v_mov_b32_e32 v81, v61
	v_add_f32_dpp v34, v34, v34 row_half_mirror row_mask:0xf bank_mask:0xf bound_ctrl:1
	v_pk_add_f32 v[78:79], v[78:79], v[80:81]
	v_and_b32_e32 v49, s0, v101
	v_add_f32_dpp v34, v34, v34 row_mirror row_mask:0xf bank_mask:0xf bound_ctrl:1
	v_pk_add_f32 v[76:77], v[76:77], v[78:79]
	v_readlane_b32 s4, v34, 16
	v_readlane_b32 s5, v34, 48
	v_add_f32_e32 v40, v76, v77
	v_readlane_b32 s0, v34, 0
	v_readlane_b32 s1, v34, 32
	v_mov_b32_e32 v76, s4
	v_mov_b32_e32 v77, s5
	v_pk_add_f32 v[76:77], s[0:1], v[76:77]
	v_pk_mov_b32 v[48:49], v[64:65], v[48:49] op_sel:[1,0]
	v_add_f32_e32 v34, v76, v77
	v_fmamk_f32 v34, v34, 0x3aaaaaab, v173
	v_cmp_gt_f32_e32 vcc, s92, v34
	s_nop 0
	v_rsq_f32_e32 v34, v34
	s_nop 0
	s_nop 0
	s_nop 1
	s_nop 1
	s_nop 0
	v_mov_b32_e32 v34, v34
	v_pk_mul_f32 v[70:71], v[70:71], v[34:35] op_sel_hi:[1,0]
	v_add_f32_dpp v36, v40, v40 quad_perm:[1,0,3,2] row_mask:0xf bank_mask:0xf bound_ctrl:1
	v_pk_mul_f32 v[46:47], v[34:35], v[46:47] op_sel_hi:[0,1]
	v_pk_mul_f32 v[74:75], v[74:75], v[34:35] op_sel:[1,0] op_sel_hi:[0,0]
	v_add_f32_dpp v36, v36, v36 quad_perm:[2,3,0,1] row_mask:0xf bank_mask:0xf bound_ctrl:1
	v_pk_mul_f32 v[70:71], v[2:3], v[70:71]
	v_pk_mul_f32 v[48:49], v[34:35], v[48:49] op_sel_hi:[0,1]
	v_add_f32_dpp v36, v36, v36 row_half_mirror row_mask:0xf bank_mask:0xf bound_ctrl:1
	v_pk_mul_f32 v[46:47], v[10:11], v[46:47]
	v_pk_mul_f32 v[42:43], v[42:43], v[34:35] op_sel_hi:[1,0]
	v_add_f32_dpp v36, v36, v36 row_mirror row_mask:0xf bank_mask:0xf bound_ctrl:1
	v_pk_mul_f32 v[74:75], v[4:5], v[74:75]
	v_readlane_b32 s4, v36, 16
	v_readlane_b32 s5, v36, 48
	v_readlane_b32 s0, v36, 0
	v_readlane_b32 s1, v36, 32
	v_mov_b32_e32 v76, s4
	v_mov_b32_e32 v77, s5
	v_pk_add_f32 v[76:77], s[0:1], v[76:77]
	v_cvt_pk_bf16_f32 v70, v70, v71
	v_cvt_pk_bf16_f32 v71, v74, v75
	global_store_dwordx2 v107, v[70:71], s[2:3] offset:1024
	v_add_f32_e32 v36, v76, v77
	v_fmamk_f32 v36, v36, 0x3aaaaaab, v173
	v_cmp_gt_f32_e32 vcc, s92, v36
	v_pk_mul_f32 v[48:49], v[12:13], v[48:49]
	v_rsq_f32_e32 v36, v36
	v_pk_mul_f32 v[42:43], v[20:21], v[42:43]
	s_nop 0
	s_nop 1
	s_nop 1
	s_nop 0
	v_mov_b32_e32 v36, v36
	v_pk_mul_f32 v[66:67], v[66:67], v[36:37] op_sel_hi:[1,0]
	v_mov_b32_e32 v44, v37
	v_mov_b32_e32 v40, v35
	v_pk_mul_f32 v[72:73], v[72:73], v[36:37] op_sel_hi:[1,0]
	v_pk_mul_f32 v[66:67], v[6:7], v[66:67]
	v_pk_mul_f32 v[44:45], v[44:45], v[34:35] op_sel_hi:[1,0]
	v_pk_mul_f32 v[34:35], v[40:41], v[36:37] op_sel_hi:[1,0]
	v_pk_mul_f32 v[72:73], v[8:9], v[72:73]
	v_cvt_pk_bf16_f32 v66, v66, v67
	v_pk_mul_f32 v[62:63], v[36:37], v[62:63] op_sel_hi:[0,1]
	v_cvt_pk_bf16_f32 v67, v72, v73
	global_store_dwordx2 v107, v[66:67], s[2:3] offset:2560
	v_pk_mul_f32 v[64:65], v[36:37], v[68:69] op_sel_hi:[0,1]
	v_cvt_pk_bf16_f32 v46, v46, v47
	v_cvt_pk_bf16_f32 v47, v48, v49
	v_pk_mul_f32 v[36:37], v[38:39], v[36:37] op_sel_hi:[1,0]
	v_pk_mul_f32 v[34:35], v[22:23], v[34:35]
	v_pk_mul_f32 v[64:65], v[16:17], v[64:65]
	v_pk_mul_f32 v[62:63], v[14:15], v[62:63]
	global_store_dwordx2 v107, v[46:47], s[2:3] offset:1536
	v_cvt_pk_bf16_f32 v46, v62, v63
	v_cvt_pk_bf16_f32 v47, v64, v65
	global_store_dwordx2 v107, v[46:47], s[2:3] offset:3072
	v_pk_mul_f32 v[44:45], v[18:19], v[44:45]
	v_pk_mul_f32 v[36:37], v[24:25], v[36:37]
	v_cvt_pk_bf16_f32 v38, v44, v45
	v_cvt_pk_bf16_f32 v39, v42, v43
	global_store_dwordx2 v107, v[38:39], s[2:3] offset:2048
	v_cvt_pk_bf16_f32 v34, v34, v35
	v_cvt_pk_bf16_f32 v35, v36, v37
	global_store_dwordx2 v107, v[34:35], s[2:3] offset:3584
	s_branch .LBB0_1030

.LBB0_1227:
	v_readlane_b32 s40, v246, 5
	v_readlane_b32 s46, v246, 11
	v_readlane_b32 s47, v246, 12
	s_mov_b32 s0, 0x24200000
	v_readlane_b32 s41, v246, 6
	v_lshl_add_u64 v[36:37], s[46:47], 0, v[34:35]
	v_add_co_u32_e32 v38, vcc, s0, v36
	v_readlane_b32 s42, v246, 7
	s_nop 0
	v_addc_co_u32_e32 v39, vcc, 0, v37, vcc
	global_load_dwordx2 v[40:41], v[38:39], off
	global_load_dwordx2 v[42:43], v[38:39], off offset:512
	global_load_dwordx2 v[44:45], v[38:39], off offset:1024
	global_load_dwordx2 v[46:47], v[38:39], off offset:1536
	v_add_co_u32_e32 v36, vcc, 0x1c200000, v36
	v_readlane_b32 s43, v246, 8
	s_nop 0
	v_addc_co_u32_e32 v37, vcc, 0, v37, vcc
	global_load_dwordx2 v[48:49], v[36:37], off
	global_load_dwordx2 v[50:51], v[36:37], off offset:512
	global_load_dwordx2 v[52:53], v[36:37], off offset:1024
	global_load_dwordx2 v[54:55], v[36:37], off offset:1536
	global_load_dwordx2 v[56:57], v[36:37], off offset:2048
	global_load_dwordx2 v[58:59], v[36:37], off offset:2560
	global_load_dwordx2 v[60:61], v[36:37], off offset:3072
	global_load_dwordx2 v[62:63], v[38:39], off offset:2048
	global_load_dwordx2 v[64:65], v[38:39], off offset:2560
	global_load_dwordx2 v[66:67], v[38:39], off offset:3072
	s_nop 0
	global_load_dwordx2 v[38:39], v[38:39], off offset:3584
	s_nop 0
	global_load_dwordx2 v[68:69], v[36:37], off offset:3584
	v_readlane_b32 s44, v246, 9
	v_readlane_b32 s45, v246, 10
	s_waitcnt vmcnt(11)
	v_lshlrev_b32_e32 v80, 16, v48
	v_and_b32_e32 v81, 0xffff0000, v48
	v_lshlrev_b32_e32 v70, 16, v40
	v_and_b32_e32 v71, 0xffff0000, v40
	v_lshlrev_b32_e32 v40, 16, v41
	v_and_b32_e32 v41, 0xffff0000, v41
	v_lshlrev_b32_e32 v77, 16, v46
	s_waitcnt vmcnt(5)
	v_lshlrev_b32_e32 v92, 16, v60
	v_and_b32_e32 v93, 0xffff0000, v60
	v_mul_f32_e32 v60, v41, v41
	v_mul_f32_e32 v76, v71, v71
	v_lshlrev_b32_e32 v73, 16, v43
	v_lshlrev_b32_e32 v72, 16, v42
	v_and_b32_e32 v43, 0xffff0000, v43
	v_and_b32_e32 v42, 0xffff0000, v42
	v_pk_fma_f32 v[98:99], v[40:41], v[40:41], v[60:61] op_sel_hi:[1,1,0]
	v_pk_fma_f32 v[100:101], v[70:71], v[70:71], v[76:77] op_sel_hi:[1,1,0]
	v_lshlrev_b32_e32 v74, 16, v44
	v_and_b32_e32 v75, 0xffff0000, v44
	v_lshlrev_b32_e32 v44, 16, v45
	v_and_b32_e32 v45, 0xffff0000, v45
	v_pk_mul_f32 v[94:95], v[42:43], v[42:43]
	v_mov_b32_e32 v97, v77
	v_mov_b32_e32 v76, v100
	v_mov_b32_e32 v96, v98
	v_and_b32_e32 v79, 0xffff0000, v46
	v_lshlrev_b32_e32 v46, 16, v47
	v_and_b32_e32 v47, 0xffff0000, v47
	v_mul_f32_e32 v78, v75, v75
	v_pk_fma_f32 v[94:95], v[72:73], v[72:73], v[94:95]
	v_pk_add_f32 v[98:99], v[100:101], v[98:99]
	v_pk_mul_f32 v[96:97], v[76:77], v[96:97]
	v_mul_f32_e32 v60, v45, v45
	v_mul_f32_e32 v1, v79, v79
	v_mul_f32_e32 v104, v46, v46
	v_mul_f32_e32 v105, v47, v47
	v_pk_fma_f32 v[102:103], v[74:75], v[74:75], v[78:79] op_sel_hi:[1,1,0]
	v_pk_add_f32 v[94:95], v[94:95], v[94:95] op_sel:[0,1] op_sel_hi:[1,0]
	v_mov_b32_e32 v99, v97
	v_pk_fma_f32 v[96:97], v[44:45], v[44:45], v[60:61] op_sel_hi:[1,1,0]
	v_mov_b32_e32 v103, v104
	v_mov_b32_e32 v95, v1
	v_mov_b32_e32 v97, v105
	v_pk_add_f32 v[94:95], v[98:99], v[94:95]
	v_pk_add_f32 v[96:97], v[102:103], v[96:97]
	s_waitcnt vmcnt(3)
	v_lshlrev_b32_e32 v101, 16, v65
	v_pk_add_f32 v[94:95], v[94:95], v[96:97]
	v_lshlrev_b32_e32 v97, 16, v63
	v_lshlrev_b32_e32 v96, 16, v62
	v_and_b32_e32 v63, 0xffff0000, v63
	v_and_b32_e32 v62, 0xffff0000, v62
	v_pk_mul_f32 v[98:99], v[62:63], v[62:63]
	v_lshlrev_b32_e32 v100, 16, v64
	v_pk_fma_f32 v[98:99], v[96:97], v[96:97], v[98:99]
	v_and_b32_e32 v65, 0xffff0000, v65
	v_pk_add_f32 v[98:99], v[98:99], v[98:99] op_sel:[0,1] op_sel_hi:[1,0]
	v_and_b32_e32 v64, 0xffff0000, v64
	s_waitcnt vmcnt(1)
	v_lshlrev_b32_e32 v107, 16, v38
	v_pk_add_f32 v[94:95], v[94:95], v[94:95] op_sel:[0,1] op_sel_hi:[1,0]
	v_pk_mul_f32 v[102:103], v[64:65], v[64:65]
	v_mov_b32_e32 v106, v94
	v_mov_b32_e32 v110, v98
	v_mov_b32_e32 v111, v107
	v_pk_fma_f32 v[102:103], v[100:101], v[100:101], v[102:103]
	v_and_b32_e32 v109, 0xffff0000, v38
	v_pk_add_f32 v[94:95], v[94:95], v[98:99]
	v_pk_mul_f32 v[98:99], v[106:107], v[110:111]
	v_and_b32_e32 v105, 0xffff0000, v66
	v_mul_f32_e32 v1, v109, v109
	v_mov_b32_e32 v95, v99
	v_pk_add_f32 v[98:99], v[102:103], v[102:103] op_sel:[0,1] op_sel_hi:[1,0]
	v_lshlrev_b32_e32 v104, 16, v66
	v_lshlrev_b32_e32 v66, 16, v67
	v_and_b32_e32 v67, 0xffff0000, v67
	v_mov_b32_e32 v99, v1
	v_mul_f32_e32 v60, v105, v105
	v_lshlrev_b32_e32 v38, 16, v39
	v_and_b32_e32 v39, 0xffff0000, v39
	v_pk_add_f32 v[94:95], v[94:95], v[98:99]
	v_pk_fma_f32 v[98:99], v[104:105], v[104:105], v[60:61] op_sel_hi:[1,1,0]
	v_mul_f32_e32 v60, v67, v67
	v_mul_f32_e32 v76, v38, v38
	v_mul_f32_e32 v78, v39, v39
	v_pk_fma_f32 v[102:103], v[66:67], v[66:67], v[60:61] op_sel_hi:[1,1,0]
	v_mov_b32_e32 v99, v76
	v_mov_b32_e32 v103, v78
	v_pk_add_f32 v[98:99], v[98:99], v[102:103]
	v_lshlrev_b32_e32 v48, 16, v49
	v_pk_add_f32 v[94:95], v[94:95], v[98:99]
	v_and_b32_e32 v49, 0xffff0000, v49
	v_add_f32_e32 v1, v94, v95
	v_lshlrev_b32_e32 v82, 16, v50
	v_and_b32_e32 v83, 0xffff0000, v50
	v_add_f32_dpp v1, v1, v1 quad_perm:[1,0,3,2] row_mask:0xf bank_mask:0xf bound_ctrl:1
	v_lshlrev_b32_e32 v50, 16, v51
	v_and_b32_e32 v51, 0xffff0000, v51
	v_add_f32_dpp v1, v1, v1 quad_perm:[2,3,0,1] row_mask:0xf bank_mask:0xf bound_ctrl:1
	v_lshlrev_b32_e32 v84, 16, v52
	v_and_b32_e32 v85, 0xffff0000, v52
	v_add_f32_dpp v1, v1, v1 row_half_mirror row_mask:0xf bank_mask:0xf bound_ctrl:1
	v_lshlrev_b32_e32 v52, 16, v53
	v_and_b32_e32 v53, 0xffff0000, v53
	v_add_f32_dpp v1, v1, v1 row_mirror row_mask:0xf bank_mask:0xf bound_ctrl:1
	v_lshlrev_b32_e32 v86, 16, v54
	v_readlane_b32 s4, v1, 16
	v_readlane_b32 s5, v1, 48
	v_readlane_b32 s0, v1, 0
	v_readlane_b32 s1, v1, 32
	v_mov_b32_e32 v94, s4
	v_mov_b32_e32 v95, s5
	v_pk_add_f32 v[94:95], s[0:1], v[94:95]
	v_and_b32_e32 v87, 0xffff0000, v54
	v_add_f32_e32 v1, v94, v95
	v_fmamk_f32 v1, v1, 0x3a000000, v173
	v_lshlrev_b32_e32 v54, 16, v55
	v_and_b32_e32 v55, 0xffff0000, v55
	v_rsq_f32_e32 v1, v1
	v_lshlrev_b32_e32 v88, 16, v56
	v_and_b32_e32 v89, 0xffff0000, v56
	v_lshlrev_b32_e32 v56, 16, v57
	v_and_b32_e32 v57, 0xffff0000, v57
	v_lshlrev_b32_e32 v90, 16, v58
	v_and_b32_e32 v91, 0xffff0000, v58
	v_lshlrev_b32_e32 v58, 16, v59
	v_and_b32_e32 v59, 0xffff0000, v59
	v_lshlrev_b32_e32 v60, 16, v61
	v_and_b32_e32 v61, 0xffff0000, v61
	v_mov_b32_e32 v108, v107
	v_mov_b32_e32 v76, v1
	v_pk_mul_f32 v[70:71], v[76:77], v[70:71] op_sel_hi:[0,1]
	v_pk_mul_f32 v[40:41], v[76:77], v[40:41] op_sel_hi:[0,1]
	v_pk_fma_f32 v[40:41], v[4:5], v[40:41], v[48:49]
	v_pk_fma_f32 v[48:49], v[2:3], v[70:71], v[80:81]
	v_mov_b32_e32 v70, v72
	v_mov_b32_e32 v71, v42
	v_mov_b32_e32 v42, v73
	v_pk_mul_f32 v[70:71], v[76:77], v[70:71] op_sel_hi:[0,1]
	v_pk_mul_f32 v[42:43], v[76:77], v[42:43] op_sel_hi:[0,1]
	v_pk_fma_f32 v[42:43], v[8:9], v[42:43], v[50:51]
	v_pk_fma_f32 v[50:51], v[6:7], v[70:71], v[82:83]
	v_pk_mul_f32 v[70:71], v[76:77], v[74:75] op_sel_hi:[0,1]
	v_pk_mul_f32 v[44:45], v[76:77], v[44:45] op_sel_hi:[0,1]
	v_mov_b32_e32 v78, v77
	v_pk_fma_f32 v[44:45], v[12:13], v[44:45], v[52:53]
	v_pk_fma_f32 v[52:53], v[10:11], v[70:71], v[84:85]
	v_pk_mul_f32 v[70:71], v[78:79], v[76:77] op_sel_hi:[1,0]
	v_pk_mul_f32 v[46:47], v[46:47], v[76:77] op_sel_hi:[1,0]
	v_pk_mul_f32 v[66:67], v[76:77], v[66:67] op_sel_hi:[0,1]
	v_pk_fma_f32 v[46:47], v[16:17], v[46:47], v[54:55]
	v_pk_fma_f32 v[54:55], v[14:15], v[70:71], v[86:87]
	v_mov_b32_e32 v70, v96
	v_mov_b32_e32 v71, v62
	v_mov_b32_e32 v62, v97
	v_pk_mul_f32 v[70:71], v[76:77], v[70:71] op_sel_hi:[0,1]
	v_pk_mul_f32 v[62:63], v[76:77], v[62:63] op_sel_hi:[0,1]
	v_pk_fma_f32 v[56:57], v[20:21], v[62:63], v[56:57]
	v_pk_fma_f32 v[62:63], v[18:19], v[70:71], v[88:89]
	v_mov_b32_e32 v70, v100
	v_mov_b32_e32 v71, v64
	v_mov_b32_e32 v64, v101
	v_pk_mul_f32 v[70:71], v[76:77], v[70:71] op_sel_hi:[0,1]
	v_pk_mul_f32 v[64:65], v[76:77], v[64:65] op_sel_hi:[0,1]
	v_pk_fma_f32 v[58:59], v[24:25], v[64:65], v[58:59]
	v_pk_fma_f32 v[64:65], v[22:23], v[70:71], v[90:91]
	v_pk_mul_f32 v[70:71], v[76:77], v[104:105] op_sel_hi:[0,1]
	s_waitcnt vmcnt(0)
	v_lshlrev_b32_e32 v94, 16, v68
	v_and_b32_e32 v95, 0xffff0000, v68
	v_lshlrev_b32_e32 v68, 16, v69
	v_and_b32_e32 v69, 0xffff0000, v69
	v_pk_fma_f32 v[60:61], v[28:29], v[66:67], v[60:61]
	v_pk_fma_f32 v[66:67], v[26:27], v[70:71], v[92:93]
	v_pk_mul_f32 v[70:71], v[108:109], v[76:77] op_sel_hi:[1,0]
	v_pk_mul_f32 v[38:39], v[38:39], v[76:77] op_sel_hi:[1,0]
	v_mul_f32_e32 v1, v49, v49
	v_pk_fma_f32 v[38:39], v[32:33], v[38:39], v[68:69]
	v_pk_fma_f32 v[68:69], v[30:31], v[70:71], v[94:95]
	v_cvt_pk_bf16_f32 v70, v48, v49
	v_cvt_pk_bf16_f32 v71, v40, v41
	v_mul_f32_e32 v41, v41, v41
	v_fmac_f32_e32 v1, v48, v48
	v_fmac_f32_e32 v41, v40, v40
	global_store_dwordx2 v[36:37], v[70:71], off
	v_add_f32_e32 v1, v1, v41
	v_cvt_pk_bf16_f32 v40, v50, v51
	v_cvt_pk_bf16_f32 v41, v42, v43
	global_store_dwordx2 v[36:37], v[40:41], off offset:512
	v_mul_f32_e32 v40, v51, v51
	v_mul_f32_e32 v41, v43, v43
	v_fmac_f32_e32 v40, v50, v50
	v_fmac_f32_e32 v41, v42, v42
	v_add_f32_e32 v40, v40, v41
	v_add_f32_e32 v1, v1, v40
	v_cvt_pk_bf16_f32 v40, v52, v53
	v_cvt_pk_bf16_f32 v41, v44, v45
	global_store_dwordx2 v[36:37], v[40:41], off offset:1024
	v_mul_f32_e32 v40, v53, v53
	v_mul_f32_e32 v41, v45, v45
	v_fmac_f32_e32 v40, v52, v52
	v_fmac_f32_e32 v41, v44, v44
	v_add_f32_e32 v40, v40, v41
	v_add_f32_e32 v1, v40, v1
	v_cvt_pk_bf16_f32 v40, v54, v55
	v_cvt_pk_bf16_f32 v41, v46, v47
	global_store_dwordx2 v[36:37], v[40:41], off offset:1536
	v_mul_f32_e32 v40, v55, v55
	v_mul_f32_e32 v41, v47, v47
	v_fmac_f32_e32 v40, v54, v54
	v_fmac_f32_e32 v41, v46, v46
	v_add_f32_e32 v40, v40, v41
	v_add_f32_e32 v1, v40, v1
	v_cvt_pk_bf16_f32 v40, v62, v63
	v_cvt_pk_bf16_f32 v41, v56, v57
	global_store_dwordx2 v[36:37], v[40:41], off offset:2048
	v_mul_f32_e32 v40, v63, v63
	v_mul_f32_e32 v41, v57, v57
	v_fmac_f32_e32 v40, v62, v62
	v_fmac_f32_e32 v41, v56, v56
	v_add_f32_e32 v40, v40, v41
	v_add_f32_e32 v1, v40, v1
	v_cvt_pk_bf16_f32 v40, v64, v65
	v_cvt_pk_bf16_f32 v41, v58, v59
	global_store_dwordx2 v[36:37], v[40:41], off offset:2560
	v_mul_f32_e32 v40, v65, v65
	v_mul_f32_e32 v41, v59, v59
	v_fmac_f32_e32 v40, v64, v64
	v_fmac_f32_e32 v41, v58, v58
	v_add_f32_e32 v40, v40, v41
	v_add_f32_e32 v1, v40, v1
	v_cvt_pk_bf16_f32 v40, v66, v67
	v_cvt_pk_bf16_f32 v41, v60, v61
	global_store_dwordx2 v[36:37], v[40:41], off offset:3072
	v_mul_f32_e32 v40, v67, v67
	v_mul_f32_e32 v41, v61, v61
	v_fmac_f32_e32 v40, v66, v66
	v_fmac_f32_e32 v41, v60, v60
	v_add_f32_e32 v40, v40, v41
	v_add_f32_e32 v1, v40, v1
	v_cvt_pk_bf16_f32 v40, v68, v69
	v_cvt_pk_bf16_f32 v41, v38, v39
	global_store_dwordx2 v[36:37], v[40:41], off offset:3584
	v_mul_f32_e32 v36, v69, v69
	v_mul_f32_e32 v37, v39, v39
	v_fmac_f32_e32 v36, v68, v68
	v_fmac_f32_e32 v37, v38, v38
	v_add_f32_e32 v36, v36, v37
	v_add_f32_e32 v1, v36, v1
	s_nop 1
	v_add_f32_dpp v1, v1, v1 quad_perm:[1,0,3,2] row_mask:0xf bank_mask:0xf bound_ctrl:1
	s_nop 1
	v_add_f32_dpp v1, v1, v1 quad_perm:[2,3,0,1] row_mask:0xf bank_mask:0xf bound_ctrl:1
	s_nop 1
	v_add_f32_dpp v1, v1, v1 row_half_mirror row_mask:0xf bank_mask:0xf bound_ctrl:1
	s_nop 1
	v_add_f32_dpp v1, v1, v1 row_mirror row_mask:0xf bank_mask:0xf bound_ctrl:1
	s_nop 0
	v_readlane_b32 s0, v1, 0
	v_readlane_b32 s9, v1, 16
	v_readlane_b32 s1, v1, 32
	v_readlane_b32 s11, v1, 48
	s_and_saveexec_b64 s[4:5], s[36:37]
	s_cbranch_execz .LBB0_1226
	v_mov_b32_e32 v36, s9
	v_mov_b32_e32 v37, s11
	v_pk_add_f32 v[36:37], s[0:1], v[36:37]
	v_readlane_b32 s40, v246, 5
	v_add_f32_e32 v1, v36, v37
	v_fmamk_f32 v1, v1, 0x3a000000, v173
	v_readlane_b32 s44, v246, 9
	v_readlane_b32 s45, v246, 10
	v_rsq_f32_e32 v1, v1
	v_readlane_b32 s46, v246, 11
	v_readlane_b32 s47, v246, 12
	s_mov_b64 s[20:21], s[44:45]
	s_mov_b64 s[22:23], s[46:47]
	v_readlane_b32 s41, v246, 6
	v_readlane_b32 s42, v246, 7
	v_readlane_b32 s43, v246, 8
	s_nop 0
	s_add_u32 s0, s22, s2
	s_addc_u32 s1, s23, s3
	v_mov_b32_e32 v1, v1
	global_store_dword v163, v1, s[0:1]
	s_branch .LBB0_1226

.LBB0_1733:
	v_readlane_b32 s40, v246, 5
	v_readlane_b32 s46, v246, 11
	v_readlane_b32 s47, v246, 12
	s_mov_b32 s0, 0x24200000
	v_readlane_b32 s41, v246, 6
	v_lshl_add_u64 v[36:37], s[46:47], 0, v[34:35]
	v_add_co_u32_e32 v38, vcc, s0, v36
	v_readlane_b32 s42, v246, 7
	s_nop 0
	v_addc_co_u32_e32 v39, vcc, 0, v37, vcc
	global_load_dwordx2 v[40:41], v[38:39], off
	global_load_dwordx2 v[42:43], v[38:39], off offset:512
	global_load_dwordx2 v[44:45], v[38:39], off offset:1024
	global_load_dwordx2 v[46:47], v[38:39], off offset:1536
	v_add_co_u32_e32 v36, vcc, 0x1c200000, v36
	v_readlane_b32 s43, v246, 8
	s_nop 0
	v_addc_co_u32_e32 v37, vcc, 0, v37, vcc
	global_load_dwordx2 v[48:49], v[36:37], off
	global_load_dwordx2 v[50:51], v[36:37], off offset:512
	global_load_dwordx2 v[52:53], v[36:37], off offset:1024
	global_load_dwordx2 v[54:55], v[36:37], off offset:1536
	global_load_dwordx2 v[56:57], v[36:37], off offset:2048
	global_load_dwordx2 v[58:59], v[36:37], off offset:2560
	global_load_dwordx2 v[60:61], v[36:37], off offset:3072
	global_load_dwordx2 v[62:63], v[38:39], off offset:2048
	global_load_dwordx2 v[64:65], v[38:39], off offset:2560
	global_load_dwordx2 v[66:67], v[38:39], off offset:3072
	s_nop 0
	global_load_dwordx2 v[38:39], v[38:39], off offset:3584
	s_nop 0
	global_load_dwordx2 v[68:69], v[36:37], off offset:3584
	v_readlane_b32 s44, v246, 9
	v_readlane_b32 s45, v246, 10
	s_waitcnt vmcnt(11)
	v_lshlrev_b32_e32 v80, 16, v48
	v_and_b32_e32 v81, 0xffff0000, v48
	v_lshlrev_b32_e32 v70, 16, v40
	v_and_b32_e32 v71, 0xffff0000, v40
	v_lshlrev_b32_e32 v40, 16, v41
	v_and_b32_e32 v41, 0xffff0000, v41
	v_lshlrev_b32_e32 v77, 16, v46
	s_waitcnt vmcnt(5)
	v_lshlrev_b32_e32 v92, 16, v60
	v_and_b32_e32 v93, 0xffff0000, v60
	v_mul_f32_e32 v60, v41, v41
	v_mul_f32_e32 v76, v71, v71
	v_lshlrev_b32_e32 v73, 16, v43
	v_lshlrev_b32_e32 v72, 16, v42
	v_and_b32_e32 v43, 0xffff0000, v43
	v_and_b32_e32 v42, 0xffff0000, v42
	v_pk_fma_f32 v[98:99], v[40:41], v[40:41], v[60:61] op_sel_hi:[1,1,0]
	v_pk_fma_f32 v[100:101], v[70:71], v[70:71], v[76:77] op_sel_hi:[1,1,0]
	v_lshlrev_b32_e32 v74, 16, v44
	v_and_b32_e32 v75, 0xffff0000, v44
	v_lshlrev_b32_e32 v44, 16, v45
	v_and_b32_e32 v45, 0xffff0000, v45
	v_pk_mul_f32 v[94:95], v[42:43], v[42:43]
	v_mov_b32_e32 v97, v77
	v_mov_b32_e32 v76, v100
	v_mov_b32_e32 v96, v98
	v_and_b32_e32 v79, 0xffff0000, v46
	v_lshlrev_b32_e32 v46, 16, v47
	v_and_b32_e32 v47, 0xffff0000, v47
	v_mul_f32_e32 v78, v75, v75
	v_pk_fma_f32 v[94:95], v[72:73], v[72:73], v[94:95]
	v_pk_add_f32 v[98:99], v[100:101], v[98:99]
	v_pk_mul_f32 v[96:97], v[76:77], v[96:97]
	v_mul_f32_e32 v60, v45, v45
	v_mul_f32_e32 v1, v79, v79
	v_mul_f32_e32 v104, v46, v46
	v_mul_f32_e32 v105, v47, v47
	v_pk_fma_f32 v[102:103], v[74:75], v[74:75], v[78:79] op_sel_hi:[1,1,0]
	v_pk_add_f32 v[94:95], v[94:95], v[94:95] op_sel:[0,1] op_sel_hi:[1,0]
	v_mov_b32_e32 v99, v97
	v_pk_fma_f32 v[96:97], v[44:45], v[44:45], v[60:61] op_sel_hi:[1,1,0]
	v_mov_b32_e32 v103, v104
	v_mov_b32_e32 v95, v1
	v_mov_b32_e32 v97, v105
	v_pk_add_f32 v[94:95], v[98:99], v[94:95]
	v_pk_add_f32 v[96:97], v[102:103], v[96:97]
	s_waitcnt vmcnt(3)
	v_lshlrev_b32_e32 v101, 16, v65
	v_pk_add_f32 v[94:95], v[94:95], v[96:97]
	v_lshlrev_b32_e32 v97, 16, v63
	v_lshlrev_b32_e32 v96, 16, v62
	v_and_b32_e32 v63, 0xffff0000, v63
	v_and_b32_e32 v62, 0xffff0000, v62
	v_pk_mul_f32 v[98:99], v[62:63], v[62:63]
	v_lshlrev_b32_e32 v100, 16, v64
	v_pk_fma_f32 v[98:99], v[96:97], v[96:97], v[98:99]
	v_and_b32_e32 v65, 0xffff0000, v65
	v_pk_add_f32 v[98:99], v[98:99], v[98:99] op_sel:[0,1] op_sel_hi:[1,0]
	v_and_b32_e32 v64, 0xffff0000, v64
	s_waitcnt vmcnt(1)
	v_lshlrev_b32_e32 v107, 16, v38
	v_pk_add_f32 v[94:95], v[94:95], v[94:95] op_sel:[0,1] op_sel_hi:[1,0]
	v_pk_mul_f32 v[102:103], v[64:65], v[64:65]
	v_mov_b32_e32 v106, v94
	v_mov_b32_e32 v110, v98
	v_mov_b32_e32 v111, v107
	v_pk_fma_f32 v[102:103], v[100:101], v[100:101], v[102:103]
	v_and_b32_e32 v109, 0xffff0000, v38
	v_pk_add_f32 v[94:95], v[94:95], v[98:99]
	v_pk_mul_f32 v[98:99], v[106:107], v[110:111]
	v_and_b32_e32 v105, 0xffff0000, v66
	v_mul_f32_e32 v1, v109, v109
	v_mov_b32_e32 v95, v99
	v_pk_add_f32 v[98:99], v[102:103], v[102:103] op_sel:[0,1] op_sel_hi:[1,0]
	v_lshlrev_b32_e32 v104, 16, v66
	v_lshlrev_b32_e32 v66, 16, v67
	v_and_b32_e32 v67, 0xffff0000, v67
	v_mov_b32_e32 v99, v1
	v_mul_f32_e32 v60, v105, v105
	v_lshlrev_b32_e32 v38, 16, v39
	v_and_b32_e32 v39, 0xffff0000, v39
	v_pk_add_f32 v[94:95], v[94:95], v[98:99]
	v_pk_fma_f32 v[98:99], v[104:105], v[104:105], v[60:61] op_sel_hi:[1,1,0]
	v_mul_f32_e32 v60, v67, v67
	v_mul_f32_e32 v76, v38, v38
	v_mul_f32_e32 v78, v39, v39
	v_pk_fma_f32 v[102:103], v[66:67], v[66:67], v[60:61] op_sel_hi:[1,1,0]
	v_mov_b32_e32 v99, v76
	v_mov_b32_e32 v103, v78
	v_pk_add_f32 v[98:99], v[98:99], v[102:103]
	v_lshlrev_b32_e32 v48, 16, v49
	v_pk_add_f32 v[94:95], v[94:95], v[98:99]
	v_and_b32_e32 v49, 0xffff0000, v49
	v_add_f32_e32 v1, v94, v95
	v_lshlrev_b32_e32 v82, 16, v50
	v_and_b32_e32 v83, 0xffff0000, v50
	v_add_f32_dpp v1, v1, v1 quad_perm:[1,0,3,2] row_mask:0xf bank_mask:0xf bound_ctrl:1
	v_lshlrev_b32_e32 v50, 16, v51
	v_and_b32_e32 v51, 0xffff0000, v51
	v_add_f32_dpp v1, v1, v1 quad_perm:[2,3,0,1] row_mask:0xf bank_mask:0xf bound_ctrl:1
	v_lshlrev_b32_e32 v84, 16, v52
	v_and_b32_e32 v85, 0xffff0000, v52
	v_add_f32_dpp v1, v1, v1 row_half_mirror row_mask:0xf bank_mask:0xf bound_ctrl:1
	v_lshlrev_b32_e32 v52, 16, v53
	v_and_b32_e32 v53, 0xffff0000, v53
	v_add_f32_dpp v1, v1, v1 row_mirror row_mask:0xf bank_mask:0xf bound_ctrl:1
	v_lshlrev_b32_e32 v86, 16, v54
	v_readlane_b32 s4, v1, 16
	v_readlane_b32 s5, v1, 48
	v_readlane_b32 s0, v1, 0
	v_readlane_b32 s1, v1, 32
	v_mov_b32_e32 v94, s4
	v_mov_b32_e32 v95, s5
	v_pk_add_f32 v[94:95], s[0:1], v[94:95]
	v_and_b32_e32 v87, 0xffff0000, v54
	v_add_f32_e32 v1, v94, v95
	v_fmamk_f32 v1, v1, 0x3a000000, v173
	v_lshlrev_b32_e32 v54, 16, v55
	v_and_b32_e32 v55, 0xffff0000, v55
	v_rsq_f32_e32 v1, v1
	v_lshlrev_b32_e32 v88, 16, v56
	v_and_b32_e32 v89, 0xffff0000, v56
	v_lshlrev_b32_e32 v56, 16, v57
	v_and_b32_e32 v57, 0xffff0000, v57
	v_lshlrev_b32_e32 v90, 16, v58
	v_and_b32_e32 v91, 0xffff0000, v58
	v_lshlrev_b32_e32 v58, 16, v59
	v_and_b32_e32 v59, 0xffff0000, v59
	v_lshlrev_b32_e32 v60, 16, v61
	v_and_b32_e32 v61, 0xffff0000, v61
	v_mov_b32_e32 v108, v107
	v_mov_b32_e32 v76, v1
	v_pk_mul_f32 v[70:71], v[76:77], v[70:71] op_sel_hi:[0,1]
	v_pk_mul_f32 v[40:41], v[76:77], v[40:41] op_sel_hi:[0,1]
	v_pk_fma_f32 v[40:41], v[4:5], v[40:41], v[48:49]
	v_pk_fma_f32 v[48:49], v[2:3], v[70:71], v[80:81]
	v_mov_b32_e32 v70, v72
	v_mov_b32_e32 v71, v42
	v_mov_b32_e32 v42, v73
	v_pk_mul_f32 v[70:71], v[76:77], v[70:71] op_sel_hi:[0,1]
	v_pk_mul_f32 v[42:43], v[76:77], v[42:43] op_sel_hi:[0,1]
	v_pk_fma_f32 v[42:43], v[8:9], v[42:43], v[50:51]
	v_pk_fma_f32 v[50:51], v[6:7], v[70:71], v[82:83]
	v_pk_mul_f32 v[70:71], v[76:77], v[74:75] op_sel_hi:[0,1]
	v_pk_mul_f32 v[44:45], v[76:77], v[44:45] op_sel_hi:[0,1]
	v_mov_b32_e32 v78, v77
	v_pk_fma_f32 v[44:45], v[12:13], v[44:45], v[52:53]
	v_pk_fma_f32 v[52:53], v[10:11], v[70:71], v[84:85]
	v_pk_mul_f32 v[70:71], v[78:79], v[76:77] op_sel_hi:[1,0]
	v_pk_mul_f32 v[46:47], v[46:47], v[76:77] op_sel_hi:[1,0]
	v_pk_mul_f32 v[66:67], v[76:77], v[66:67] op_sel_hi:[0,1]
	v_pk_fma_f32 v[46:47], v[16:17], v[46:47], v[54:55]
	v_pk_fma_f32 v[54:55], v[14:15], v[70:71], v[86:87]
	v_mov_b32_e32 v70, v96
	v_mov_b32_e32 v71, v62
	v_mov_b32_e32 v62, v97
	v_pk_mul_f32 v[70:71], v[76:77], v[70:71] op_sel_hi:[0,1]
	v_pk_mul_f32 v[62:63], v[76:77], v[62:63] op_sel_hi:[0,1]
	v_pk_fma_f32 v[56:57], v[20:21], v[62:63], v[56:57]
	v_pk_fma_f32 v[62:63], v[18:19], v[70:71], v[88:89]
	v_mov_b32_e32 v70, v100
	v_mov_b32_e32 v71, v64
	v_mov_b32_e32 v64, v101
	v_pk_mul_f32 v[70:71], v[76:77], v[70:71] op_sel_hi:[0,1]
	v_pk_mul_f32 v[64:65], v[76:77], v[64:65] op_sel_hi:[0,1]
	v_pk_fma_f32 v[58:59], v[24:25], v[64:65], v[58:59]
	v_pk_fma_f32 v[64:65], v[22:23], v[70:71], v[90:91]
	v_pk_mul_f32 v[70:71], v[76:77], v[104:105] op_sel_hi:[0,1]
	s_waitcnt vmcnt(0)
	v_lshlrev_b32_e32 v94, 16, v68
	v_and_b32_e32 v95, 0xffff0000, v68
	v_lshlrev_b32_e32 v68, 16, v69
	v_and_b32_e32 v69, 0xffff0000, v69
	v_pk_fma_f32 v[60:61], v[28:29], v[66:67], v[60:61]
	v_pk_fma_f32 v[66:67], v[26:27], v[70:71], v[92:93]
	v_pk_mul_f32 v[70:71], v[108:109], v[76:77] op_sel_hi:[1,0]
	v_pk_mul_f32 v[38:39], v[38:39], v[76:77] op_sel_hi:[1,0]
	v_mul_f32_e32 v1, v49, v49
	v_pk_fma_f32 v[38:39], v[32:33], v[38:39], v[68:69]
	v_pk_fma_f32 v[68:69], v[30:31], v[70:71], v[94:95]
	v_cvt_pk_bf16_f32 v70, v48, v49
	v_cvt_pk_bf16_f32 v71, v40, v41
	v_mul_f32_e32 v41, v41, v41
	v_fmac_f32_e32 v1, v48, v48
	v_fmac_f32_e32 v41, v40, v40
	global_store_dwordx2 v[36:37], v[70:71], off
	v_add_f32_e32 v1, v1, v41
	v_cvt_pk_bf16_f32 v40, v50, v51
	v_cvt_pk_bf16_f32 v41, v42, v43
	global_store_dwordx2 v[36:37], v[40:41], off offset:512
	v_mul_f32_e32 v40, v51, v51
	v_mul_f32_e32 v41, v43, v43
	v_fmac_f32_e32 v40, v50, v50
	v_fmac_f32_e32 v41, v42, v42
	v_add_f32_e32 v40, v40, v41
	v_add_f32_e32 v1, v1, v40
	v_cvt_pk_bf16_f32 v40, v52, v53
	v_cvt_pk_bf16_f32 v41, v44, v45
	global_store_dwordx2 v[36:37], v[40:41], off offset:1024
	v_mul_f32_e32 v40, v53, v53
	v_mul_f32_e32 v41, v45, v45
	v_fmac_f32_e32 v40, v52, v52
	v_fmac_f32_e32 v41, v44, v44
	v_add_f32_e32 v40, v40, v41
	v_add_f32_e32 v1, v40, v1
	v_cvt_pk_bf16_f32 v40, v54, v55
	v_cvt_pk_bf16_f32 v41, v46, v47
	global_store_dwordx2 v[36:37], v[40:41], off offset:1536
	v_mul_f32_e32 v40, v55, v55
	v_mul_f32_e32 v41, v47, v47
	v_fmac_f32_e32 v40, v54, v54
	v_fmac_f32_e32 v41, v46, v46
	v_add_f32_e32 v40, v40, v41
	v_add_f32_e32 v1, v40, v1
	v_cvt_pk_bf16_f32 v40, v62, v63
	v_cvt_pk_bf16_f32 v41, v56, v57
	global_store_dwordx2 v[36:37], v[40:41], off offset:2048
	v_mul_f32_e32 v40, v63, v63
	v_mul_f32_e32 v41, v57, v57
	v_fmac_f32_e32 v40, v62, v62
	v_fmac_f32_e32 v41, v56, v56
	v_add_f32_e32 v40, v40, v41
	v_add_f32_e32 v1, v40, v1
	v_cvt_pk_bf16_f32 v40, v64, v65
	v_cvt_pk_bf16_f32 v41, v58, v59
	global_store_dwordx2 v[36:37], v[40:41], off offset:2560
	v_mul_f32_e32 v40, v65, v65
	v_mul_f32_e32 v41, v59, v59
	v_fmac_f32_e32 v40, v64, v64
	v_fmac_f32_e32 v41, v58, v58
	v_add_f32_e32 v40, v40, v41
	v_add_f32_e32 v1, v40, v1
	v_cvt_pk_bf16_f32 v40, v66, v67
	v_cvt_pk_bf16_f32 v41, v60, v61
	global_store_dwordx2 v[36:37], v[40:41], off offset:3072
	v_mul_f32_e32 v40, v67, v67
	v_mul_f32_e32 v41, v61, v61
	v_fmac_f32_e32 v40, v66, v66
	v_fmac_f32_e32 v41, v60, v60
	v_add_f32_e32 v40, v40, v41
	v_add_f32_e32 v1, v40, v1
	v_cvt_pk_bf16_f32 v40, v68, v69
	v_cvt_pk_bf16_f32 v41, v38, v39
	global_store_dwordx2 v[36:37], v[40:41], off offset:3584
	v_mul_f32_e32 v36, v69, v69
	v_mul_f32_e32 v37, v39, v39
	v_fmac_f32_e32 v36, v68, v68
	v_fmac_f32_e32 v37, v38, v38
	v_add_f32_e32 v36, v36, v37
	v_add_f32_e32 v1, v36, v1
	s_nop 1
	v_add_f32_dpp v1, v1, v1 quad_perm:[1,0,3,2] row_mask:0xf bank_mask:0xf bound_ctrl:1
	s_nop 1
	v_add_f32_dpp v1, v1, v1 quad_perm:[2,3,0,1] row_mask:0xf bank_mask:0xf bound_ctrl:1
	s_nop 1
	v_add_f32_dpp v1, v1, v1 row_half_mirror row_mask:0xf bank_mask:0xf bound_ctrl:1
	s_nop 1
	v_add_f32_dpp v1, v1, v1 row_mirror row_mask:0xf bank_mask:0xf bound_ctrl:1
	s_nop 0
	v_readlane_b32 s0, v1, 0
	v_readlane_b32 s9, v1, 16
	v_readlane_b32 s1, v1, 32
	v_readlane_b32 s11, v1, 48
	s_and_saveexec_b64 s[4:5], s[38:39]
	s_cbranch_execz .LBB0_1732
	v_mov_b32_e32 v36, s9
	v_mov_b32_e32 v37, s11
	v_pk_add_f32 v[36:37], s[0:1], v[36:37]
	v_readlane_b32 s40, v246, 5
	v_add_f32_e32 v1, v36, v37
	v_fmamk_f32 v1, v1, 0x3a000000, v173
	v_readlane_b32 s44, v246, 9
	v_readlane_b32 s45, v246, 10
	v_rsq_f32_e32 v1, v1
	v_readlane_b32 s46, v246, 11
	v_readlane_b32 s47, v246, 12
	s_mov_b64 s[20:21], s[44:45]
	s_mov_b64 s[22:23], s[46:47]
	v_readlane_b32 s41, v246, 6
	v_readlane_b32 s42, v246, 7
	v_readlane_b32 s43, v246, 8
	s_nop 0
	s_add_u32 s0, s22, s2
	s_addc_u32 s1, s23, s3
	v_mov_b32_e32 v1, v1
	global_store_dword v163, v1, s[0:1]
	s_branch .LBB0_1732

.LBB0_2004:
	s_ashr_i32 s3, s2, 31
	s_lshl_b64 s[0:1], s[2:3], 12
	v_lshl_add_u64 v[74:75], v[38:39], 0, s[0:1]
	global_load_dwordx2 v[42:43], v[74:75], off
	global_load_dwordx2 v[46:47], v[74:75], off offset:512
	global_load_dwordx2 v[48:49], v[74:75], off offset:1024
	global_load_dwordx2 v[50:51], v[74:75], off offset:1536
	global_load_dwordx2 v[52:53], v[74:75], off offset:2048
	global_load_dwordx2 v[54:55], v[74:75], off offset:2560
	global_load_dwordx2 v[44:45], v[74:75], off offset:3072
	v_lshl_add_u64 v[56:57], v[40:41], 0, s[0:1]
	global_load_dwordx2 v[58:59], v[56:57], off
	global_load_dwordx2 v[60:61], v[56:57], off offset:512
	global_load_dwordx2 v[62:63], v[56:57], off offset:1024
	global_load_dwordx2 v[64:65], v[56:57], off offset:1536
	global_load_dwordx2 v[66:67], v[56:57], off offset:2048
	global_load_dwordx2 v[68:69], v[56:57], off offset:2560
	global_load_dwordx2 v[70:71], v[74:75], off offset:3584
	global_load_dwordx2 v[72:73], v[56:57], off offset:3072
	s_nop 0
	global_load_dwordx2 v[56:57], v[56:57], off offset:3584
	s_waitcnt vmcnt(15)
	v_lshlrev_b32_e32 v76, 16, v42
	v_and_b32_e32 v77, 0xffff0000, v42
	v_lshlrev_b32_e32 v78, 16, v43
	v_and_b32_e32 v79, 0xffff0000, v43
	s_waitcnt vmcnt(7)
	v_lshlrev_b32_e32 v93, 16, v61
	v_lshlrev_b32_e32 v88, 16, v54
	v_and_b32_e32 v89, 0xffff0000, v54
	v_lshlrev_b32_e32 v90, 16, v55
	v_and_b32_e32 v91, 0xffff0000, v55
	v_lshlrev_b32_e32 v54, 16, v58
	v_and_b32_e32 v55, 0xffff0000, v58
	v_lshlrev_b32_e32 v58, 16, v59
	v_and_b32_e32 v59, 0xffff0000, v59
	v_lshlrev_b32_e32 v42, 16, v44
	v_and_b32_e32 v43, 0xffff0000, v44
	v_lshlrev_b32_e32 v92, 16, v60
	v_and_b32_e32 v61, 0xffff0000, v61
	v_and_b32_e32 v60, 0xffff0000, v60
	s_waitcnt vmcnt(5)
	v_lshlrev_b32_e32 v97, 16, v64
	v_mul_f32_e32 v44, v59, v59
	v_mul_f32_e32 v96, v55, v55
	v_lshlrev_b32_e32 v94, 16, v62
	v_and_b32_e32 v95, 0xffff0000, v62
	v_lshlrev_b32_e32 v62, 16, v63
	v_and_b32_e32 v63, 0xffff0000, v63
	v_and_b32_e32 v99, 0xffff0000, v64
	v_lshlrev_b32_e32 v100, 16, v65
	v_and_b32_e32 v101, 0xffff0000, v65
	v_pk_mul_f32 v[64:65], v[60:61], v[60:61]
	v_pk_fma_f32 v[108:109], v[58:59], v[58:59], v[44:45] op_sel_hi:[1,1,0]
	v_pk_fma_f32 v[110:111], v[54:55], v[54:55], v[96:97] op_sel_hi:[1,1,0]
	s_waitcnt vmcnt(4)
	v_and_b32_e32 v105, 0xffff0000, v67
	v_mov_b32_e32 v107, v97
	v_mul_f32_e32 v98, v95, v95
	v_mul_f32_e32 v104, v63, v63
	v_pk_fma_f32 v[64:65], v[92:93], v[92:93], v[64:65]
	v_mov_b32_e32 v96, v110
	v_mov_b32_e32 v106, v108
	v_lshlrev_b32_e32 v103, 16, v67
	v_mul_f32_e32 v1, v99, v99
	v_mul_f32_e32 v35, v100, v100
	v_mul_f32_e32 v67, v101, v101
	v_pk_fma_f32 v[112:113], v[94:95], v[94:95], v[98:99] op_sel_hi:[1,1,0]
	v_pk_fma_f32 v[114:115], v[62:63], v[62:63], v[104:105] op_sel_hi:[1,1,0]
	v_pk_add_f32 v[108:109], v[110:111], v[108:109]
	v_pk_add_f32 v[64:65], v[64:65], v[64:65] op_sel:[0,1] op_sel_hi:[1,0]
	v_pk_mul_f32 v[106:107], v[96:97], v[106:107]
	v_mov_b32_e32 v113, v35
	v_mov_b32_e32 v115, v67
	v_mov_b32_e32 v65, v1
	v_mov_b32_e32 v109, v107
	v_and_b32_e32 v104, 0xffff0000, v66
	v_lshlrev_b32_e32 v102, 16, v66
	v_pk_add_f32 v[110:111], v[112:113], v[114:115]
	v_pk_add_f32 v[64:65], v[108:109], v[64:65]
	v_pk_mul_f32 v[66:67], v[104:105], v[104:105]
	v_pk_add_f32 v[64:65], v[64:65], v[110:111]
	v_pk_fma_f32 v[66:67], v[102:103], v[102:103], v[66:67]
	s_waitcnt vmcnt(3)
	v_and_b32_e32 v109, 0xffff0000, v69
	v_pk_add_f32 v[66:67], v[66:67], v[66:67] op_sel:[0,1] op_sel_hi:[1,0]
	v_and_b32_e32 v108, 0xffff0000, v68
	s_waitcnt vmcnt(0)
	v_lshlrev_b32_e32 v115, 16, v56
	v_and_b32_e32 v117, 0xffff0000, v56
	v_lshlrev_b32_e32 v118, 16, v57
	v_and_b32_e32 v119, 0xffff0000, v57
	v_pk_add_f32 v[56:57], v[64:65], v[64:65] op_sel:[0,1] op_sel_hi:[1,0]
	v_lshlrev_b32_e32 v107, 16, v69
	v_lshlrev_b32_e32 v106, 16, v68
	v_pk_mul_f32 v[68:69], v[108:109], v[108:109]
	v_mov_b32_e32 v114, v56
	v_mov_b32_e32 v64, v66
	v_mov_b32_e32 v65, v115
	v_pk_fma_f32 v[68:69], v[106:107], v[106:107], v[68:69]
	v_pk_add_f32 v[56:57], v[56:57], v[66:67]
	v_pk_mul_f32 v[64:65], v[114:115], v[64:65]
	v_and_b32_e32 v111, 0xffff0000, v72
	v_mul_f32_e32 v1, v117, v117
	v_mov_b32_e32 v57, v65
	v_pk_add_f32 v[64:65], v[68:69], v[68:69] op_sel:[0,1] op_sel_hi:[1,0]
	v_lshlrev_b32_e32 v110, 16, v72
	v_and_b32_e32 v113, 0xffff0000, v73
	v_mov_b32_e32 v65, v1
	v_mul_f32_e32 v44, v111, v111
	v_lshlrev_b32_e32 v112, 16, v73
	v_pk_add_f32 v[56:57], v[56:57], v[64:65]
	v_pk_fma_f32 v[64:65], v[110:111], v[110:111], v[44:45] op_sel_hi:[1,1,0]
	v_mul_f32_e32 v44, v113, v113
	v_mul_f32_e32 v35, v118, v118
	v_mul_f32_e32 v72, v119, v119
	v_pk_fma_f32 v[66:67], v[112:113], v[112:113], v[44:45] op_sel_hi:[1,1,0]
	v_mov_b32_e32 v65, v35
	v_mov_b32_e32 v67, v72
	v_pk_add_f32 v[64:65], v[64:65], v[66:67]
	v_lshlrev_b32_e32 v120, 16, v70
	v_pk_add_f32 v[56:57], v[56:57], v[64:65]
	v_and_b32_e32 v121, 0xffff0000, v70
	v_add_f32_e32 v1, v56, v57
	v_lshlrev_b32_e32 v122, 16, v71
	v_and_b32_e32 v123, 0xffff0000, v71
	v_add_f32_dpp v1, v1, v1 quad_perm:[1,0,3,2] row_mask:0xf bank_mask:0xf bound_ctrl:1
	v_lshlrev_b32_e32 v80, 16, v46
	v_and_b32_e32 v81, 0xffff0000, v46
	v_add_f32_dpp v1, v1, v1 quad_perm:[2,3,0,1] row_mask:0xf bank_mask:0xf bound_ctrl:1
	v_lshlrev_b32_e32 v46, 16, v47
	v_and_b32_e32 v47, 0xffff0000, v47
	v_add_f32_dpp v1, v1, v1 row_half_mirror row_mask:0xf bank_mask:0xf bound_ctrl:1
	v_lshlrev_b32_e32 v82, 16, v48
	v_and_b32_e32 v83, 0xffff0000, v48
	v_add_f32_dpp v1, v1, v1 row_mirror row_mask:0xf bank_mask:0xf bound_ctrl:1
	v_lshlrev_b32_e32 v48, 16, v49
	v_readlane_b32 s4, v1, 16
	v_readlane_b32 s5, v1, 48
	v_readlane_b32 s0, v1, 0
	v_readlane_b32 s1, v1, 32
	v_mov_b32_e32 v56, s4
	v_mov_b32_e32 v57, s5
	v_pk_add_f32 v[56:57], s[0:1], v[56:57]
	v_and_b32_e32 v49, 0xffff0000, v49
	v_add_f32_e32 v1, v56, v57
	v_fmamk_f32 v1, v1, 0x3a000000, v173
	v_mov_b32_e32 v98, v97
	v_lshlrev_b32_e32 v84, 16, v50
	v_rsq_f32_e32 v1, v1
	v_and_b32_e32 v85, 0xffff0000, v50
	v_lshlrev_b32_e32 v50, 16, v51
	v_and_b32_e32 v51, 0xffff0000, v51
	v_lshlrev_b32_e32 v86, 16, v52
	v_and_b32_e32 v87, 0xffff0000, v52
	v_lshlrev_b32_e32 v52, 16, v53
	v_and_b32_e32 v53, 0xffff0000, v53
	v_lshlrev_b32_e32 v44, 16, v45
	v_and_b32_e32 v45, 0xffff0000, v45
	v_mov_b32_e32 v116, v115
	v_mov_b32_e32 v96, v1
	v_pk_mul_f32 v[54:55], v[96:97], v[54:55] op_sel_hi:[0,1]
	v_pk_mul_f32 v[56:57], v[96:97], v[58:59] op_sel_hi:[0,1]
	v_pk_fma_f32 v[70:71], v[4:5], v[56:57], v[78:79]
	v_pk_fma_f32 v[72:73], v[2:3], v[54:55], v[76:77]
	v_mov_b32_e32 v54, v92
	v_mov_b32_e32 v55, v60
	v_mov_b32_e32 v60, v93
	v_pk_mul_f32 v[54:55], v[96:97], v[54:55] op_sel_hi:[0,1]
	v_pk_mul_f32 v[56:57], v[96:97], v[60:61] op_sel_hi:[0,1]
	v_cvt_pk_bf16_f32 v76, v72, v73
	v_mul_f32_e32 v1, v73, v73
	v_mul_f32_e32 v35, v71, v71
	v_pk_fma_f32 v[66:67], v[8:9], v[56:57], v[46:47]
	v_pk_fma_f32 v[68:69], v[6:7], v[54:55], v[80:81]
	v_cvt_pk_bf16_f32 v77, v70, v71
	global_store_dwordx2 v[74:75], v[76:77], off
	v_fmac_f32_e32 v1, v72, v72
	v_fmac_f32_e32 v35, v70, v70
	v_cvt_pk_bf16_f32 v76, v68, v69
	v_add_f32_e32 v1, v1, v35
	v_cvt_pk_bf16_f32 v77, v66, v67
	global_store_dwordx2 v[74:75], v[76:77], off offset:512
	v_mul_f32_e32 v35, v69, v69
	v_mul_f32_e32 v76, v67, v67
	v_pk_mul_f32 v[46:47], v[96:97], v[94:95] op_sel_hi:[0,1]
	v_pk_mul_f32 v[54:55], v[96:97], v[62:63] op_sel_hi:[0,1]
	v_fmac_f32_e32 v35, v68, v68
	v_fmac_f32_e32 v76, v66, v66
	v_pk_fma_f32 v[62:63], v[12:13], v[54:55], v[48:49]
	v_pk_fma_f32 v[64:65], v[10:11], v[46:47], v[82:83]
	v_add_f32_e32 v35, v35, v76
	v_cvt_pk_bf16_f32 v76, v64, v65
	v_add_f32_e32 v1, v1, v35
	v_cvt_pk_bf16_f32 v77, v62, v63
	global_store_dwordx2 v[74:75], v[76:77], off offset:1024
	v_mul_f32_e32 v35, v65, v65
	v_mul_f32_e32 v76, v63, v63
	v_pk_mul_f32 v[46:47], v[98:99], v[96:97] op_sel_hi:[1,0]
	v_pk_mul_f32 v[48:49], v[100:101], v[96:97] op_sel_hi:[1,0]
	v_fmac_f32_e32 v35, v64, v64
	v_fmac_f32_e32 v76, v62, v62
	v_pk_fma_f32 v[56:57], v[16:17], v[48:49], v[50:51]
	v_pk_fma_f32 v[60:61], v[14:15], v[46:47], v[84:85]
	v_add_f32_e32 v35, v35, v76
	v_cvt_pk_bf16_f32 v76, v60, v61
	v_mov_b32_e32 v46, v102
	v_mov_b32_e32 v47, v104
	v_mov_b32_e32 v104, v103
	v_add_f32_e32 v1, v35, v1
	v_cvt_pk_bf16_f32 v77, v56, v57
	global_store_dwordx2 v[74:75], v[76:77], off offset:1536
	v_mul_f32_e32 v35, v61, v61
	v_mul_f32_e32 v76, v57, v57
	v_pk_mul_f32 v[46:47], v[96:97], v[46:47] op_sel_hi:[0,1]
	v_pk_mul_f32 v[48:49], v[96:97], v[104:105] op_sel_hi:[0,1]
	v_fmac_f32_e32 v35, v60, v60
	v_fmac_f32_e32 v76, v56, v56
	v_pk_fma_f32 v[54:55], v[20:21], v[48:49], v[52:53]
	v_pk_fma_f32 v[58:59], v[18:19], v[46:47], v[86:87]
	v_add_f32_e32 v35, v35, v76
	v_cvt_pk_bf16_f32 v76, v58, v59
	v_mov_b32_e32 v46, v106
	v_mov_b32_e32 v47, v108
	v_mov_b32_e32 v108, v107
	v_add_f32_e32 v1, v35, v1
	v_cvt_pk_bf16_f32 v77, v54, v55
	global_store_dwordx2 v[74:75], v[76:77], off offset:2048
	v_mul_f32_e32 v35, v59, v59
	v_mul_f32_e32 v76, v55, v55
	v_pk_mul_f32 v[46:47], v[96:97], v[46:47] op_sel_hi:[0,1]
	v_pk_mul_f32 v[48:49], v[96:97], v[108:109] op_sel_hi:[0,1]
	v_fmac_f32_e32 v35, v58, v58
	v_fmac_f32_e32 v76, v54, v54
	v_pk_fma_f32 v[50:51], v[24:25], v[48:49], v[90:91]
	v_pk_fma_f32 v[52:53], v[22:23], v[46:47], v[88:89]
	v_add_f32_e32 v35, v35, v76
	v_cvt_pk_bf16_f32 v76, v52, v53
	v_add_f32_e32 v1, v35, v1
	v_cvt_pk_bf16_f32 v77, v50, v51
	global_store_dwordx2 v[74:75], v[76:77], off offset:2560
	v_mul_f32_e32 v35, v53, v53
	v_mul_f32_e32 v76, v51, v51
	v_pk_mul_f32 v[48:49], v[96:97], v[110:111] op_sel_hi:[0,1]
	v_pk_mul_f32 v[46:47], v[96:97], v[112:113] op_sel_hi:[0,1]
	v_fmac_f32_e32 v35, v52, v52
	v_fmac_f32_e32 v76, v50, v50
	v_pk_fma_f32 v[46:47], v[28:29], v[46:47], v[44:45]
	v_pk_fma_f32 v[48:49], v[26:27], v[48:49], v[42:43]
	v_add_f32_e32 v35, v35, v76
	v_add_f32_e32 v1, v35, v1
	v_mul_f32_e32 v35, v49, v49
	v_mul_f32_e32 v76, v47, v47
	v_pk_mul_f32 v[44:45], v[116:117], v[96:97] op_sel_hi:[1,0]
	v_pk_mul_f32 v[42:43], v[118:119], v[96:97] op_sel_hi:[1,0]
	v_fmac_f32_e32 v35, v48, v48
	v_fmac_f32_e32 v76, v46, v46
	v_pk_fma_f32 v[42:43], v[32:33], v[42:43], v[122:123]
	v_pk_fma_f32 v[44:45], v[30:31], v[44:45], v[120:121]
	v_add_f32_e32 v35, v35, v76
	v_add_f32_e32 v1, v35, v1
	v_mul_f32_e32 v35, v45, v45
	v_mul_f32_e32 v76, v43, v43
	v_fmac_f32_e32 v35, v44, v44
	v_fmac_f32_e32 v76, v42, v42
	v_add_f32_e32 v35, v35, v76
	v_add_f32_e32 v1, v35, v1
	v_cvt_pk_bf16_f32 v76, v48, v49
	v_cvt_pk_bf16_f32 v77, v46, v47
	global_store_dwordx2 v[74:75], v[76:77], off offset:3072
	s_nop 0
	v_add_f32_dpp v1, v1, v1 quad_perm:[1,0,3,2] row_mask:0xf bank_mask:0xf bound_ctrl:1
	s_nop 1
	v_add_f32_dpp v1, v1, v1 quad_perm:[2,3,0,1] row_mask:0xf bank_mask:0xf bound_ctrl:1
	s_nop 1
	v_add_f32_dpp v1, v1, v1 row_half_mirror row_mask:0xf bank_mask:0xf bound_ctrl:1
	s_nop 1
	v_add_f32_dpp v1, v1, v1 row_mirror row_mask:0xf bank_mask:0xf bound_ctrl:1
	s_nop 0
	v_readlane_b32 s1, v1, 16
	v_readlane_b32 s5, v1, 48
	v_readlane_b32 s0, v1, 0
	v_readlane_b32 s4, v1, 32
	v_mov_b32_e32 v1, s1
	v_mov_b32_e32 v35, s5
	v_add_f32_e32 v1, s0, v1
	v_add_f32_e32 v35, s4, v35
	v_add_f32_e32 v1, v1, v35
	v_fmamk_f32 v1, v1, 0x3a000000, v173
	s_nop 1
	v_rsq_f32_e32 v1, v1
	s_nop 0
	s_nop 0
	s_nop 1
	v_cvt_pk_bf16_f32 v76, v44, v45
	v_cvt_pk_bf16_f32 v77, v42, v43
	global_store_dwordx2 v[74:75], v[76:77], off offset:3584
	s_nop 0
	s_nop 0
	v_mov_b32_e32 v1, v1
	s_and_saveexec_b64 s[0:1], s[36:37]
	s_cbranch_execz .LBB0_2006
	s_lshl_b64 s[4:5], s[2:3], 2
	v_readlane_b32 s3, v245, 9
	s_add_u32 s4, s3, s4
	v_readlane_b32 s3, v245, 10
	s_addc_u32 s5, s3, s5
	global_store_dword v163, v1, s[4:5]
.LBB0_2006:
	s_or_b64 exec, exec, s[0:1]
	s_add_i32 s4, s2, s86
	s_cmp_ge_i32 s4, s25
	s_cselect_b64 s[18:19], -1, 0
	s_and_b64 vcc, exec, s[18:19]
	s_cbranch_vccnz .LBB0_2010
	s_ashr_i32 s5, s4, 31
	s_lshl_b64 s[0:1], s[4:5], 12
	v_lshl_add_u64 v[106:107], v[38:39], 0, s[0:1]
	global_load_dwordx2 v[76:77], v[106:107], off
	global_load_dwordx2 v[78:79], v[106:107], off offset:512
	global_load_dwordx2 v[80:81], v[106:107], off offset:1024
	global_load_dwordx2 v[82:83], v[106:107], off offset:1536
	global_load_dwordx2 v[84:85], v[106:107], off offset:2048
	global_load_dwordx2 v[86:87], v[106:107], off offset:2560
	global_load_dwordx2 v[74:75], v[106:107], off offset:3072
	v_lshl_add_u64 v[88:89], v[40:41], 0, s[0:1]
	global_load_dwordx2 v[90:91], v[88:89], off
	global_load_dwordx2 v[92:93], v[88:89], off offset:512
	global_load_dwordx2 v[94:95], v[88:89], off offset:1024
	global_load_dwordx2 v[96:97], v[88:89], off offset:1536
	global_load_dwordx2 v[98:99], v[88:89], off offset:2048
	global_load_dwordx2 v[100:101], v[88:89], off offset:2560
	global_load_dwordx2 v[102:103], v[106:107], off offset:3584
	global_load_dwordx2 v[104:105], v[88:89], off offset:3072
	s_nop 0
	global_load_dwordx2 v[88:89], v[88:89], off offset:3584
	s_waitcnt vmcnt(15)
	v_lshlrev_b32_e32 v108, 16, v76
	s_waitcnt vmcnt(7)
	v_lshlrev_b32_e32 v125, 16, v93
	v_lshlrev_b32_e32 v124, 16, v92
	v_and_b32_e32 v93, 0xffff0000, v93
	v_and_b32_e32 v92, 0xffff0000, v92
	v_lshlrev_b32_e32 v118, 16, v86
	v_and_b32_e32 v119, 0xffff0000, v86
	v_lshlrev_b32_e32 v120, 16, v87
	v_and_b32_e32 v121, 0xffff0000, v87
	v_lshlrev_b32_e32 v86, 16, v90
	v_and_b32_e32 v87, 0xffff0000, v90
	v_lshlrev_b32_e32 v90, 16, v91
	v_and_b32_e32 v91, 0xffff0000, v91
	v_lshlrev_b32_e32 v122, 16, v74
	v_and_b32_e32 v123, 0xffff0000, v74
	s_waitcnt vmcnt(5)
	v_lshlrev_b32_e32 v129, 16, v96
	v_mul_f32_e32 v74, v91, v91
	v_mul_f32_e32 v128, v87, v87
	v_lshlrev_b32_e32 v126, 16, v94
	v_and_b32_e32 v127, 0xffff0000, v94
	v_lshlrev_b32_e32 v94, 16, v95
	v_and_b32_e32 v95, 0xffff0000, v95
	v_and_b32_e32 v131, 0xffff0000, v96
	v_lshlrev_b32_e32 v132, 16, v97
	v_and_b32_e32 v133, 0xffff0000, v97
	v_pk_mul_f32 v[96:97], v[92:93], v[92:93]
	v_pk_fma_f32 v[140:141], v[90:91], v[90:91], v[74:75] op_sel_hi:[1,1,0]
	v_pk_fma_f32 v[142:143], v[86:87], v[86:87], v[128:129] op_sel_hi:[1,1,0]
	s_waitcnt vmcnt(4)
	v_and_b32_e32 v137, 0xffff0000, v99
	v_mov_b32_e32 v139, v129
	v_mul_f32_e32 v130, v127, v127
	v_mul_f32_e32 v136, v95, v95
	v_pk_fma_f32 v[96:97], v[124:125], v[124:125], v[96:97]
	v_mov_b32_e32 v128, v142
	v_mov_b32_e32 v138, v140
	v_lshlrev_b32_e32 v135, 16, v99
	v_mul_f32_e32 v35, v131, v131
	v_mul_f32_e32 v99, v132, v132
	v_mul_f32_e32 v148, v133, v133
	v_pk_fma_f32 v[144:145], v[126:127], v[126:127], v[130:131] op_sel_hi:[1,1,0]
	v_pk_fma_f32 v[146:147], v[94:95], v[94:95], v[136:137] op_sel_hi:[1,1,0]
	v_pk_add_f32 v[140:141], v[142:143], v[140:141]
	v_pk_add_f32 v[96:97], v[96:97], v[96:97] op_sel:[0,1] op_sel_hi:[1,0]
	v_pk_mul_f32 v[138:139], v[128:129], v[138:139]
	v_mov_b32_e32 v145, v99
	v_mov_b32_e32 v147, v148
	v_mov_b32_e32 v97, v35
	v_mov_b32_e32 v141, v139
	v_and_b32_e32 v136, 0xffff0000, v98
	v_lshlrev_b32_e32 v134, 16, v98
	v_pk_add_f32 v[142:143], v[144:145], v[146:147]
	v_pk_add_f32 v[96:97], v[140:141], v[96:97]
	v_pk_mul_f32 v[98:99], v[136:137], v[136:137]
	v_pk_add_f32 v[96:97], v[96:97], v[142:143]
	v_pk_fma_f32 v[98:99], v[134:135], v[134:135], v[98:99]
	s_waitcnt vmcnt(3)
	v_and_b32_e32 v141, 0xffff0000, v101
	v_pk_add_f32 v[98:99], v[98:99], v[98:99] op_sel:[0,1] op_sel_hi:[1,0]
	v_and_b32_e32 v140, 0xffff0000, v100
	s_waitcnt vmcnt(0)
	v_lshlrev_b32_e32 v147, 16, v88
	v_and_b32_e32 v149, 0xffff0000, v88
	v_lshlrev_b32_e32 v150, 16, v89
	v_and_b32_e32 v151, 0xffff0000, v89
	v_pk_add_f32 v[88:89], v[96:97], v[96:97] op_sel:[0,1] op_sel_hi:[1,0]
	v_lshlrev_b32_e32 v139, 16, v101
	v_lshlrev_b32_e32 v138, 16, v100
	v_pk_mul_f32 v[100:101], v[140:141], v[140:141]
	v_mov_b32_e32 v146, v88
	v_mov_b32_e32 v96, v98
	v_mov_b32_e32 v97, v147
	v_pk_fma_f32 v[100:101], v[138:139], v[138:139], v[100:101]
	v_pk_add_f32 v[88:89], v[88:89], v[98:99]
	v_pk_mul_f32 v[96:97], v[146:147], v[96:97]
	v_and_b32_e32 v143, 0xffff0000, v104
	v_mul_f32_e32 v35, v149, v149
	v_mov_b32_e32 v89, v97
	v_pk_add_f32 v[96:97], v[100:101], v[100:101] op_sel:[0,1] op_sel_hi:[1,0]
	v_lshlrev_b32_e32 v142, 16, v104
	v_and_b32_e32 v145, 0xffff0000, v105
	v_mov_b32_e32 v97, v35
	v_mul_f32_e32 v74, v143, v143
	v_lshlrev_b32_e32 v144, 16, v105
	v_pk_add_f32 v[88:89], v[88:89], v[96:97]
	v_pk_fma_f32 v[96:97], v[142:143], v[142:143], v[74:75] op_sel_hi:[1,1,0]
	v_mul_f32_e32 v74, v145, v145
	v_mul_f32_e32 v104, v150, v150
	v_mul_f32_e32 v105, v151, v151
	v_pk_fma_f32 v[98:99], v[144:145], v[144:145], v[74:75] op_sel_hi:[1,1,0]
	v_mov_b32_e32 v97, v104
	v_mov_b32_e32 v99, v105
	v_pk_add_f32 v[96:97], v[96:97], v[98:99]
	v_and_b32_e32 v109, 0xffff0000, v76
	v_pk_add_f32 v[88:89], v[88:89], v[96:97]
	v_lshlrev_b32_e32 v76, 16, v77
	v_add_f32_e32 v35, v88, v89
	v_and_b32_e32 v77, 0xffff0000, v77
	v_lshlrev_b32_e32 v152, 16, v102
	v_add_f32_dpp v35, v35, v35 quad_perm:[1,0,3,2] row_mask:0xf bank_mask:0xf bound_ctrl:1
	v_and_b32_e32 v153, 0xffff0000, v102
	v_lshlrev_b32_e32 v154, 16, v103
	v_add_f32_dpp v35, v35, v35 quad_perm:[2,3,0,1] row_mask:0xf bank_mask:0xf bound_ctrl:1
	v_and_b32_e32 v155, 0xffff0000, v103
	v_lshlrev_b32_e32 v110, 16, v78
	v_add_f32_dpp v35, v35, v35 row_half_mirror row_mask:0xf bank_mask:0xf bound_ctrl:1
	v_and_b32_e32 v111, 0xffff0000, v78
	v_lshlrev_b32_e32 v78, 16, v79
	v_add_f32_dpp v35, v35, v35 row_mirror row_mask:0xf bank_mask:0xf bound_ctrl:1
	v_and_b32_e32 v79, 0xffff0000, v79
	v_readlane_b32 s3, v35, 16
	v_readlane_b32 s8, v35, 48
	v_readlane_b32 s0, v35, 0
	v_readlane_b32 s1, v35, 32
	v_mov_b32_e32 v88, s3
	v_mov_b32_e32 v89, s8
	v_pk_add_f32 v[88:89], s[0:1], v[88:89]
	v_lshlrev_b32_e32 v112, 16, v80
	v_add_f32_e32 v35, v88, v89
	v_fmamk_f32 v35, v35, 0x3a000000, v173
	v_and_b32_e32 v113, 0xffff0000, v80
	v_lshlrev_b32_e32 v80, 16, v81
	v_rsq_f32_e32 v35, v35
	v_and_b32_e32 v81, 0xffff0000, v81
	v_mov_b32_e32 v130, v129
	v_lshlrev_b32_e32 v114, 16, v82
	v_and_b32_e32 v115, 0xffff0000, v82
	v_lshlrev_b32_e32 v82, 16, v83
	v_and_b32_e32 v83, 0xffff0000, v83
	v_lshlrev_b32_e32 v116, 16, v84
	v_and_b32_e32 v117, 0xffff0000, v84
	v_lshlrev_b32_e32 v84, 16, v85
	v_and_b32_e32 v85, 0xffff0000, v85
	v_lshlrev_b32_e32 v74, 16, v75
	v_mov_b32_e32 v128, v35
	v_pk_mul_f32 v[88:89], v[128:129], v[90:91] op_sel_hi:[0,1]
	v_pk_fma_f32 v[102:103], v[4:5], v[88:89], v[76:77]
	v_mov_b32_e32 v76, v124
	v_mov_b32_e32 v77, v92
	v_pk_mul_f32 v[86:87], v[128:129], v[86:87] op_sel_hi:[0,1]
	v_pk_mul_f32 v[76:77], v[128:129], v[76:77] op_sel_hi:[0,1]
	v_mov_b32_e32 v92, v125
	v_pk_fma_f32 v[104:105], v[2:3], v[86:87], v[108:109]
	v_pk_mul_f32 v[86:87], v[128:129], v[92:93] op_sel_hi:[0,1]
	v_pk_fma_f32 v[100:101], v[6:7], v[76:77], v[110:111]
	v_cvt_pk_bf16_f32 v108, v104, v105
	v_cvt_pk_bf16_f32 v109, v102, v103
	v_pk_fma_f32 v[98:99], v[8:9], v[86:87], v[78:79]
	v_pk_mul_f32 v[76:77], v[128:129], v[126:127] op_sel_hi:[0,1]
	global_store_dwordx2 v[106:107], v[108:109], off
	v_cvt_pk_bf16_f32 v108, v100, v101
	v_cvt_pk_bf16_f32 v109, v98, v99
	v_mov_b32_e32 v110, v105
	v_mov_b32_e32 v111, v101
	v_pk_fma_f32 v[96:97], v[10:11], v[76:77], v[112:113]
	global_store_dwordx2 v[106:107], v[108:109], off offset:512
	v_mov_b32_e32 v108, v104
	v_mov_b32_e32 v109, v100
	v_pk_mul_f32 v[110:111], v[110:111], v[110:111]
	v_mov_b32_e32 v112, v103
	v_mov_b32_e32 v113, v99
	v_pk_fma_f32 v[108:109], v[108:109], v[108:109], v[110:111]
	v_mov_b32_e32 v110, v102
	v_mov_b32_e32 v111, v98
	v_pk_mul_f32 v[112:113], v[112:113], v[112:113]
	v_pk_mul_f32 v[78:79], v[128:129], v[94:95] op_sel_hi:[0,1]
	v_pk_fma_f32 v[110:111], v[110:111], v[110:111], v[112:113]
	v_pk_fma_f32 v[94:95], v[12:13], v[78:79], v[80:81]
	v_pk_add_f32 v[108:109], v[108:109], v[110:111]
	v_cvt_pk_bf16_f32 v110, v96, v97
	v_cvt_pk_bf16_f32 v111, v94, v95
	v_pk_mul_f32 v[76:77], v[130:131], v[128:129] op_sel_hi:[1,0]
	global_store_dwordx2 v[106:107], v[110:111], off offset:1024
	v_pk_mul_f32 v[110:111], v[94:95], v[94:95]
	v_pk_mul_f32 v[112:113], v[96:97], v[96:97]
	v_pk_mul_f32 v[78:79], v[132:133], v[128:129] op_sel_hi:[1,0]
	v_pk_fma_f32 v[92:93], v[14:15], v[76:77], v[114:115]
	v_pk_add_f32 v[108:109], v[108:109], v[108:109] op_sel_hi:[0,1]
	v_pk_mov_b32 v[114:115], v[112:113], v[110:111] op_sel:[1,0]
	v_mov_b32_e32 v113, v111
	v_pk_fma_f32 v[90:91], v[16:17], v[78:79], v[82:83]
	v_mov_b32_e32 v76, v134
	v_mov_b32_e32 v77, v136
	v_mov_b32_e32 v136, v135
	v_pk_add_f32 v[110:111], v[114:115], v[112:113]
	v_cvt_pk_bf16_f32 v112, v92, v93
	v_cvt_pk_bf16_f32 v113, v90, v91
	v_mul_f32_e32 v108, v92, v92
	v_pk_mul_f32 v[76:77], v[128:129], v[76:77] op_sel_hi:[0,1]
	v_pk_mul_f32 v[78:79], v[128:129], v[136:137] op_sel_hi:[0,1]
	global_store_dwordx2 v[106:107], v[112:113], off offset:1536
	v_pk_fma_f32 v[112:113], v[92:93], v[92:93], v[108:109] op_sel_hi:[1,1,0]
	v_mul_f32_e32 v108, v90, v90
	v_pk_fma_f32 v[86:87], v[20:21], v[78:79], v[84:85]
	v_pk_fma_f32 v[88:89], v[18:19], v[76:77], v[116:117]
	v_pk_add_f32 v[110:111], v[110:111], v[110:111] op_sel_hi:[0,1]
	v_pk_fma_f32 v[114:115], v[90:91], v[90:91], v[108:109] op_sel_hi:[1,1,0]
	v_mov_b32_e32 v76, v138
	v_mov_b32_e32 v77, v140
	v_mov_b32_e32 v140, v139
	v_mul_f32_e32 v112, v88, v88
	v_mul_f32_e32 v114, v89, v89
	v_mul_f32_e32 v110, v86, v86
	v_mul_f32_e32 v108, v87, v87
	v_pk_mul_f32 v[76:77], v[128:129], v[76:77] op_sel_hi:[0,1]
	v_pk_mul_f32 v[78:79], v[128:129], v[140:141] op_sel_hi:[0,1]
	v_pk_add_f32 v[112:113], v[112:113], v[114:115]
	v_pk_add_f32 v[108:109], v[110:111], v[108:109]
	v_pk_fma_f32 v[82:83], v[24:25], v[78:79], v[120:121]
	v_pk_fma_f32 v[84:85], v[22:23], v[76:77], v[118:119]
	v_pk_mul_f32 v[76:77], v[128:129], v[142:143] op_sel_hi:[0,1]
	v_cvt_pk_bf16_f32 v116, v88, v89
	v_cvt_pk_bf16_f32 v117, v86, v87
	global_store_dwordx2 v[106:107], v[116:117], off offset:2048
	v_pk_add_f32 v[108:109], v[112:113], v[108:109]
	v_cvt_pk_bf16_f32 v110, v84, v85
	v_cvt_pk_bf16_f32 v111, v82, v83
	v_and_b32_e32 v75, 0xffff0000, v75
	v_pk_mul_f32 v[78:79], v[128:129], v[144:145] op_sel_hi:[0,1]
	v_pk_fma_f32 v[80:81], v[26:27], v[76:77], v[122:123]
	v_pk_add_f32 v[108:109], v[108:109], v[108:109] op_sel_hi:[0,1]
	global_store_dwordx2 v[106:107], v[110:111], off offset:2560
	v_pk_mul_f32 v[110:111], v[82:83], v[82:83]
	v_pk_mul_f32 v[112:113], v[84:85], v[84:85]
	v_pk_fma_f32 v[78:79], v[28:29], v[78:79], v[74:75]
	v_mov_b32_e32 v148, v147
	v_pk_mov_b32 v[114:115], v[112:113], v[110:111] op_sel:[1,0]
	v_mov_b32_e32 v113, v111
	v_mul_f32_e32 v108, v80, v80
	v_pk_mul_f32 v[76:77], v[148:149], v[128:129] op_sel_hi:[1,0]
	v_pk_mul_f32 v[74:75], v[150:151], v[128:129] op_sel_hi:[1,0]
	v_pk_add_f32 v[110:111], v[114:115], v[112:113]
	v_pk_fma_f32 v[112:113], v[80:81], v[80:81], v[108:109] op_sel_hi:[1,1,0]
	v_mul_f32_e32 v108, v78, v78
	v_pk_fma_f32 v[74:75], v[32:33], v[74:75], v[154:155]
	v_pk_fma_f32 v[76:77], v[30:31], v[76:77], v[152:153]
	v_pk_add_f32 v[110:111], v[110:111], v[110:111] op_sel_hi:[0,1]
	v_pk_fma_f32 v[114:115], v[78:79], v[78:79], v[108:109] op_sel_hi:[1,1,0]
	v_mul_f32_e32 v112, v76, v76
	v_mul_f32_e32 v114, v77, v77
	v_mul_f32_e32 v110, v74, v74
	v_mul_f32_e32 v108, v75, v75
	v_pk_add_f32 v[112:113], v[112:113], v[114:115]
	v_pk_add_f32 v[108:109], v[110:111], v[108:109]
	s_nop 0
	v_pk_add_f32 v[108:109], v[112:113], v[108:109]
	s_nop 0
	v_add_f32_e32 v35, v108, v109
	s_nop 1
	v_add_f32_dpp v35, v35, v35 quad_perm:[1,0,3,2] row_mask:0xf bank_mask:0xf bound_ctrl:1
	s_nop 1
	v_add_f32_dpp v35, v35, v35 quad_perm:[2,3,0,1] row_mask:0xf bank_mask:0xf bound_ctrl:1
	s_nop 1
	v_add_f32_dpp v35, v35, v35 row_half_mirror row_mask:0xf bank_mask:0xf bound_ctrl:1
	s_nop 1
	v_add_f32_dpp v35, v35, v35 row_mirror row_mask:0xf bank_mask:0xf bound_ctrl:1
	s_nop 0
	v_readlane_b32 s3, v35, 16
	v_readlane_b32 s8, v35, 48
	v_readlane_b32 s0, v35, 0
	v_readlane_b32 s1, v35, 32
	v_mov_b32_e32 v108, s3
	v_mov_b32_e32 v109, s8
	v_pk_add_f32 v[108:109], s[0:1], v[108:109]
	s_nop 0
	v_add_f32_e32 v35, v108, v109
	v_fmamk_f32 v35, v35, 0x3a000000, v173
	s_nop 1
	v_rsq_f32_e32 v35, v35
	v_cvt_pk_bf16_f32 v108, v80, v81
	v_cvt_pk_bf16_f32 v109, v78, v79
	global_store_dwordx2 v[106:107], v[108:109], off offset:3072
	s_nop 0
	s_nop 1
	s_nop 1
	v_cvt_pk_bf16_f32 v108, v76, v77
	v_cvt_pk_bf16_f32 v109, v74, v75
	global_store_dwordx2 v[106:107], v[108:109], off offset:3584
	v_mov_b32_e32 v35, v35
	s_and_saveexec_b64 s[0:1], s[36:37]
	s_cbranch_execz .LBB0_2009
	s_lshl_b64 s[8:9], s[4:5], 2
	v_readlane_b32 s3, v245, 9
	s_add_u32 s8, s3, s8
	v_readlane_b32 s3, v245, 10
	s_addc_u32 s9, s3, s9
	global_store_dword v163, v35, s[8:9]

.LBB0_2020:
	v_add_co_u32_e32 v40, vcc, 0xf8000000, v36
	global_load_dwordx2 v[72:73], v[36:37], off offset:-3584
	global_load_dwordx2 v[76:77], v[36:37], off offset:-3072
	global_load_dwordx2 v[80:81], v[36:37], off offset:-2560
	global_load_dwordx2 v[82:83], v[36:37], off offset:-2048
	v_addc_co_u32_e32 v41, vcc, -1, v37, vcc
	global_load_dwordx2 v[38:39], v[40:41], off offset:-3584
	global_load_dwordx2 v[42:43], v[40:41], off offset:-1024
	s_add_i32 s2, s2, s86
	s_cmp_lt_i32 s2, s25
	global_load_dwordx2 v[50:51], v[40:41], off offset:-512
	global_load_dwordx2 v[102:103], v[36:37], off offset:-512
	global_load_dwordx2 v[106:107], v[36:37], off
	s_waitcnt vmcnt(8)
	v_lshlrev_b32_e32 v70, 16, v72
	v_and_b32_e32 v71, 0xffff0000, v72
	v_lshlrev_b32_e32 v72, 16, v73
	v_and_b32_e32 v73, 0xffff0000, v73
	v_mul_f32_e32 v74, v73, v73
	v_pk_fma_f32 v[88:89], v[72:73], v[72:73], v[74:75] op_sel_hi:[1,1,0]
	s_waitcnt vmcnt(4)
	v_lshlrev_b32_e32 v60, 16, v38
	v_and_b32_e32 v61, 0xffff0000, v38
	v_lshlrev_b32_e32 v68, 16, v39
	v_and_b32_e32 v69, 0xffff0000, v39
	global_load_dwordx2 v[38:39], v[40:41], off offset:-3072
	v_lshlrev_b32_e32 v75, 16, v77
	v_lshlrev_b32_e32 v74, 16, v76
	v_and_b32_e32 v77, 0xffff0000, v77
	v_and_b32_e32 v76, 0xffff0000, v76
	v_and_b32_e32 v85, 0xffff0000, v82
	v_mul_f32_e32 v84, v71, v71
	v_pk_mul_f32 v[78:79], v[76:77], v[76:77]
	v_lshlrev_b32_e32 v87, 16, v82
	v_pk_fma_f32 v[92:93], v[70:71], v[70:71], v[84:85] op_sel_hi:[1,1,0]
	v_pk_fma_f32 v[90:91], v[74:75], v[74:75], v[78:79]
	v_mov_b32_e32 v86, v92
	v_mov_b32_e32 v94, v88
	v_mov_b32_e32 v95, v87
	v_and_b32_e32 v79, 0xffff0000, v80
	v_mul_f32_e32 v1, v85, v85
	v_pk_add_f32 v[88:89], v[92:93], v[88:89]
	v_pk_mul_f32 v[92:93], v[86:87], v[94:95]
	v_pk_add_f32 v[90:91], v[90:91], v[90:91] op_sel:[0,1] op_sel_hi:[1,0]
	v_lshlrev_b32_e32 v78, 16, v80
	v_lshlrev_b32_e32 v80, 16, v81
	v_and_b32_e32 v81, 0xffff0000, v81
	v_mov_b32_e32 v89, v93
	v_mov_b32_e32 v91, v1
	v_mul_f32_e32 v84, v79, v79
	v_lshlrev_b32_e32 v82, 16, v83
	v_and_b32_e32 v83, 0xffff0000, v83
	v_pk_add_f32 v[88:89], v[88:89], v[90:91]
	v_pk_fma_f32 v[90:91], v[78:79], v[78:79], v[84:85] op_sel_hi:[1,1,0]
	v_mul_f32_e32 v84, v81, v81
	v_mul_f32_e32 v96, v82, v82
	v_mul_f32_e32 v97, v83, v83
	v_pk_fma_f32 v[92:93], v[80:81], v[80:81], v[84:85] op_sel_hi:[1,1,0]
	v_mov_b32_e32 v91, v96
	v_mov_b32_e32 v93, v97
	v_pk_add_f32 v[90:91], v[90:91], v[92:93]
	global_load_dwordx2 v[96:97], v[36:37], off offset:-1024
	v_pk_add_f32 v[88:89], v[88:89], v[90:91]
	global_load_dwordx2 v[90:91], v[36:37], off offset:-1536
	s_waitcnt vmcnt(6)
	v_lshlrev_b32_e32 v46, 16, v43
	v_and_b32_e32 v47, 0xffff0000, v43
	v_pk_add_f32 v[88:89], v[88:89], v[88:89] op_sel:[0,1] op_sel_hi:[1,0]
	v_lshl_add_u64 v[36:37], v[36:37], 0, s[88:89]
	v_mov_b32_e32 v108, v88
	s_waitcnt vmcnt(5)
	v_and_b32_e32 v43, 0xffff0000, v50
	v_lshlrev_b32_e32 v52, 16, v51
	v_and_b32_e32 v53, 0xffff0000, v51
	s_waitcnt vmcnt(3)
	v_lshlrev_b32_e32 v109, 16, v106
	v_and_b32_e32 v111, 0xffff0000, v106
	v_and_b32_e32 v105, 0xffff0000, v102
	v_lshlrev_b32_e32 v104, 16, v102
	v_lshlrev_b32_e32 v102, 16, v103
	v_and_b32_e32 v103, 0xffff0000, v103
	v_lshlrev_b32_e32 v106, 16, v107
	v_and_b32_e32 v107, 0xffff0000, v107
	v_mov_b32_e32 v113, v109
	v_mul_f32_e32 v1, v111, v111
	v_mul_f32_e32 v84, v105, v105
	v_mul_f32_e32 v86, v106, v106
	v_mul_f32_e32 v110, v107, v107
	s_waitcnt vmcnt(2)
	v_lshlrev_b32_e32 v48, 16, v38
	v_and_b32_e32 v49, 0xffff0000, v38
	v_lshlrev_b32_e32 v62, 16, v39
	v_and_b32_e32 v63, 0xffff0000, v39
	global_load_dwordx2 v[38:39], v[40:41], off offset:-2560
	s_waitcnt vmcnt(2)
	v_lshlrev_b32_e32 v99, 16, v97
	v_lshlrev_b32_e32 v98, 16, v96
	s_waitcnt vmcnt(1)
	v_lshlrev_b32_e32 v93, 16, v91
	v_lshlrev_b32_e32 v92, 16, v90
	v_and_b32_e32 v91, 0xffff0000, v91
	v_and_b32_e32 v90, 0xffff0000, v90
	v_pk_mul_f32 v[94:95], v[90:91], v[90:91]
	v_and_b32_e32 v97, 0xffff0000, v97
	v_pk_fma_f32 v[94:95], v[92:93], v[92:93], v[94:95]
	v_and_b32_e32 v96, 0xffff0000, v96
	v_pk_add_f32 v[94:95], v[94:95], v[94:95] op_sel:[0,1] op_sel_hi:[1,0]
	v_pk_mul_f32 v[100:101], v[96:97], v[96:97]
	v_mov_b32_e32 v112, v94
	v_pk_fma_f32 v[100:101], v[98:99], v[98:99], v[100:101]
	v_pk_add_f32 v[88:89], v[88:89], v[94:95]
	v_pk_mul_f32 v[94:95], v[108:109], v[112:113]
	s_waitcnt vmcnt(0)
	v_lshlrev_b32_e32 v56, 16, v38
	v_and_b32_e32 v57, 0xffff0000, v38
	v_lshlrev_b32_e32 v66, 16, v39
	v_and_b32_e32 v67, 0xffff0000, v39
	global_load_dwordx2 v[38:39], v[40:41], off offset:-2048
	v_mov_b32_e32 v89, v95
	v_pk_add_f32 v[94:95], v[100:101], v[100:101] op_sel:[0,1] op_sel_hi:[1,0]
	s_waitcnt vmcnt(0)
	v_lshlrev_b32_e32 v54, 16, v38
	v_and_b32_e32 v55, 0xffff0000, v38
	v_lshlrev_b32_e32 v64, 16, v39
	v_and_b32_e32 v65, 0xffff0000, v39
	global_load_dwordx2 v[38:39], v[40:41], off offset:-1536
	v_mov_b32_e32 v95, v1
	v_pk_add_f32 v[88:89], v[88:89], v[94:95]
	v_pk_fma_f32 v[94:95], v[104:105], v[104:105], v[84:85] op_sel_hi:[1,1,0]
	v_mul_f32_e32 v84, v103, v103
	v_pk_fma_f32 v[100:101], v[102:103], v[102:103], v[84:85] op_sel_hi:[1,1,0]
	v_mov_b32_e32 v95, v86
	v_mov_b32_e32 v101, v110
	v_pk_add_f32 v[94:95], v[94:95], v[100:101]
	v_mov_b32_e32 v110, v109
	v_pk_add_f32 v[88:89], v[88:89], v[94:95]
	s_waitcnt vmcnt(0)
	v_lshlrev_b32_e32 v44, 16, v38
	v_and_b32_e32 v45, 0xffff0000, v38
	v_lshlrev_b32_e32 v58, 16, v39
	v_and_b32_e32 v59, 0xffff0000, v39
	v_lshlrev_b32_e32 v38, 16, v42
	v_and_b32_e32 v39, 0xffff0000, v42
	v_lshlrev_b32_e32 v42, 16, v50
	global_load_dwordx2 v[50:51], v[40:41], off
	v_add_f32_e32 v1, v88, v89
	s_waitcnt vmcnt(0)
	v_lshlrev_b32_e32 v40, 16, v50
	v_add_f32_dpp v1, v1, v1 quad_perm:[1,0,3,2] row_mask:0xf bank_mask:0xf bound_ctrl:1
	v_and_b32_e32 v41, 0xffff0000, v50
	v_lshlrev_b32_e32 v50, 16, v51
	v_add_f32_dpp v1, v1, v1 quad_perm:[2,3,0,1] row_mask:0xf bank_mask:0xf bound_ctrl:1
	v_and_b32_e32 v51, 0xffff0000, v51
	s_nop 0
	v_add_f32_dpp v1, v1, v1 row_half_mirror row_mask:0xf bank_mask:0xf bound_ctrl:1
	s_nop 1
	v_add_f32_dpp v1, v1, v1 row_mirror row_mask:0xf bank_mask:0xf bound_ctrl:1
	s_nop 0
	v_readlane_b32 s3, v1, 16
	v_readlane_b32 s4, v1, 48
	v_readlane_b32 s0, v1, 0
	v_readlane_b32 s1, v1, 32
	v_mov_b32_e32 v88, s3
	v_mov_b32_e32 v89, s4
	v_pk_add_f32 v[88:89], s[0:1], v[88:89]
	s_nop 0
	v_add_f32_e32 v1, v88, v89
	v_fmamk_f32 v1, v1, 0x3a000000, v173
	v_cmp_gt_f32_e32 vcc, s92, v1
	s_nop 0
	v_rsq_f32_e32 v1, v1
	s_nop 0
	s_nop 0
	s_nop 1
	s_nop 1
	s_nop 0
	v_mov_b32_e32 v86, v1
	v_pk_mul_f32 v[88:89], v[86:87], v[70:71] op_sel_hi:[0,1]
	v_pk_mul_f32 v[70:71], v[86:87], v[72:73] op_sel_hi:[0,1]
	v_pk_fma_f32 v[70:71], v[4:5], v[70:71], v[68:69]
	v_pk_fma_f32 v[68:69], v[2:3], v[88:89], v[60:61]
	v_mov_b32_e32 v60, v74
	v_mov_b32_e32 v61, v76
	v_mov_b32_e32 v76, v75
	v_pk_mul_f32 v[60:61], v[86:87], v[60:61] op_sel_hi:[0,1]
	v_pk_mul_f32 v[72:73], v[86:87], v[76:77] op_sel_hi:[0,1]
	v_pk_fma_f32 v[62:63], v[8:9], v[72:73], v[62:63]
	v_pk_fma_f32 v[60:61], v[6:7], v[60:61], v[48:49]
	v_pk_mul_f32 v[48:49], v[86:87], v[78:79] op_sel_hi:[0,1]
	v_pk_mul_f32 v[72:73], v[86:87], v[80:81] op_sel_hi:[0,1]
	v_mov_b32_e32 v84, v87
	v_pk_fma_f32 v[74:75], v[12:13], v[72:73], v[66:67]
	v_pk_fma_f32 v[72:73], v[10:11], v[48:49], v[56:57]
	v_pk_mul_f32 v[48:49], v[84:85], v[86:87] op_sel_hi:[1,0]
	v_pk_mul_f32 v[56:57], v[82:83], v[86:87] op_sel_hi:[1,0]
	v_pk_fma_f32 v[54:55], v[14:15], v[48:49], v[54:55]
	v_mov_b32_e32 v48, v92
	v_mov_b32_e32 v49, v90
	v_mov_b32_e32 v90, v93
	v_pk_fma_f32 v[56:57], v[16:17], v[56:57], v[64:65]
	v_pk_mul_f32 v[48:49], v[86:87], v[48:49] op_sel_hi:[0,1]
	v_pk_mul_f32 v[64:65], v[86:87], v[90:91] op_sel_hi:[0,1]
	v_pk_fma_f32 v[66:67], v[20:21], v[64:65], v[58:59]
	v_pk_fma_f32 v[64:65], v[18:19], v[48:49], v[44:45]
	v_mov_b32_e32 v44, v98
	v_mov_b32_e32 v45, v96
	v_pk_mul_f32 v[44:45], v[86:87], v[44:45] op_sel_hi:[0,1]
	v_mov_b32_e32 v96, v99
	v_pk_mul_f32 v[48:49], v[86:87], v[96:97] op_sel_hi:[0,1]
	v_pk_fma_f32 v[44:45], v[22:23], v[44:45], v[38:39]
	v_pk_mul_f32 v[38:39], v[86:87], v[104:105] op_sel_hi:[0,1]
	v_pk_fma_f32 v[46:47], v[24:25], v[48:49], v[46:47]
	v_pk_mul_f32 v[48:49], v[86:87], v[102:103] op_sel_hi:[0,1]
	v_pk_fma_f32 v[76:77], v[26:27], v[38:39], v[42:43]
	v_pk_mul_f32 v[38:39], v[110:111], v[86:87] op_sel_hi:[1,0]
	v_pk_mul_f32 v[42:43], v[106:107], v[86:87] op_sel_hi:[1,0]
	v_pk_fma_f32 v[78:79], v[28:29], v[48:49], v[52:53]
	v_pk_fma_f32 v[42:43], v[32:33], v[42:43], v[50:51]
	v_pk_fma_f32 v[40:41], v[30:31], v[38:39], v[40:41]
	global_store_dwordx4 v[34:35], v[68:71], off offset:-4096
	global_store_dwordx4 v[34:35], v[60:63], off offset:-3072
	global_store_dwordx4 v[34:35], v[72:75], off offset:-2048
	global_store_dwordx4 v[34:35], v[54:57], off offset:-1024
	global_store_dwordx4 v[34:35], v[64:67], off
	global_store_dwordx4 v[34:35], v[44:47], off offset:1024
	global_store_dwordx4 v[34:35], v[76:79], off offset:2048
	global_store_dwordx4 v[34:35], v[40:43], off offset:3072
	v_lshl_add_u64 v[34:35], v[34:35], 0, s[90:91]
	s_cbranch_scc1 .LBB0_2020
